# v28 + rope-table loads issued only by the lanes that use them (EXEC masked to fq<2)
# baseline (speedup 1.0000x reference)
;     __device__ __forceinline__ void operator()(const f32x4 (&acc)[2][2][4][2], const Unit& u, int wr, int wc, int fr, int fq, PG8_LAS float* stash, int par, PG8_LAS unsigned char* stg, const Unit& un) const {
;     ...
;                     for (int i = 0; i < 4; ++i) { v[i] = acc[ai][bj][m][0][i] * rs; v[4 + i] = acc[ai][bj][m][1][i] * rs; }
;                     if (kind <= 1 && bj == 0) {
;                         const f32x4 c0 = *(const f32x4*)(cs + pos * 16), c1 = *(const f32x4*)(cs + pos * 16 + 4), s0 = *(const f32x4*)(cs + pos * 16 + 8), s1 = *(const f32x4*)(cs + pos * 16 + 12);
; #pragma unroll
;                         for (int i = 0; i < 8; ++i) {
;                             const float c = i < 4 ? c0[i & 3] : c1[i & 3], s = i < 4 ? s0[i & 3] : s1[i & 3];
;                             const float pr = peer_x16(v[i], fq);
;                             const float r = (fq == 0) ? (v[i] * c - pr * s) : (v[i] * c + pr * s);
;                             v[i] = (fq < 2) ? r : v[i];
;                         }
;                     }
;                     if (kind == 0) {
; #pragma unroll
;                         for (int i = 0; i < 8; ++i) v[i] *= C2Q;
;                     }
;                     { u32x4 w; w.x = cvt_pk_bf16(v[0], v[1]); w.y = cvt_pk_bf16(v[2], v[3]); w.z = cvt_pk_bf16(v[4], v[5]); w.w = cvt_pk_bf16(v[6], v[7]);
;                       *(PG8_LAS u32x4*)(stg + fr * 144 + fq * 16 + bj * 64) = w; }
;                 }
;                 {
;                     int kind;
;                     if (odd) kind = (u.pn < 6) ? 0 : (u.pn == 6 ? 1 : 2);
;                     else     kind = (u.pn < 2) ? 0 : (u.pn == 2 ? (wc < 2 ? 1 : 2) : 3);
; #pragma unroll
;                     for (int i = 0; i < 2; ++i) { const int c = fq * 16 + fr + 64 * i, rr = c >> 3, pc = c & 7;
;                         const u32x4 w = *(const PG8_LAS u32x4*)(stg + rr * 144 + pc * 16);
;                         const int rowc = row - fr + rr, posc = rowc & 4095;
;                         if (kind == 1 || kind == 2) {
;                             bf16_t* dst = (kind == 1) ? kd : vt;
;                             if (odd) *(u32x4*)(dst + (size_t)(b * 4 + wc) * (4096 * 64) + (size_t)((posc & 15) * 256 + (posc >> 4)) * 64 + pc * 8) = w;
;                             else     *(u32x4*)(dst + (size_t)(b * 2 + (wc & 1)) * (4096 * 64) + (size_t)posc * 64 + pc * 8) = w;
.Lipe_Q:
	s_add_i32 s44, s19, 0
	s_and_b32 s44, s44, 0xfff
	v_or_b32_e32 v0, s44, v141
	v_lshlrev_b32_e32 v0, 6, v0
	s_mov_b64 s[44:45], exec
	s_and_b64 exec, exec, s[38:39]
	global_load_dwordx4 v[154:157], v0, s[62:63]
	global_load_dwordx4 v[158:161], v0, s[62:63] offset:16
	global_load_dwordx4 v[162:165], v0, s[62:63] offset:32
	global_load_dwordx4 v[166:169], v0, s[62:63] offset:48
	s_mov_b64 exec, s[44:45]
	s_add_i32 s44, s19, 16
	s_and_b32 s44, s44, 0xfff
	v_or_b32_e32 v0, s44, v141
	v_lshlrev_b32_e32 v0, 6, v0
	s_mov_b64 s[44:45], exec
	s_and_b64 exec, exec, s[38:39]
	global_load_dwordx4 v[218:221], v0, s[62:63]
	global_load_dwordx4 v[222:225], v0, s[62:63] offset:16
	global_load_dwordx4 v[226:229], v0, s[62:63] offset:32
	global_load_dwordx4 v[230:233], v0, s[62:63] offset:48
	s_mov_b64 exec, s[44:45]
	v_pk_mul_f32 v[118:119], v[118:119], v[152:153] op_sel_hi:[1,0]
	v_pk_mul_f32 v[120:121], v[120:121], v[152:153] op_sel_hi:[1,0]
	v_pk_mul_f32 v[114:115], v[114:115], v[152:153] op_sel_hi:[1,0]
	v_pk_mul_f32 v[116:117], v[116:117], v[152:153] op_sel_hi:[1,0]
	v_pk_mul_f32 v[118:119], v[118:119], s[30:31] op_sel_hi:[1,0]
	v_pk_mul_f32 v[120:121], v[120:121], s[30:31] op_sel_hi:[1,0]
	v_pk_mul_f32 v[114:115], v[114:115], s[30:31] op_sel_hi:[1,0]
	v_pk_mul_f32 v[116:117], v[116:117], s[30:31] op_sel_hi:[1,0]
	v_cvt_pk_bf16_f32 v118, v118, v119
	v_cvt_pk_bf16_f32 v119, v120, v121
	v_cvt_pk_bf16_f32 v120, v114, v115
	v_cvt_pk_bf16_f32 v121, v116, v117
	v_pk_mul_f32 v[126:127], v[126:127], v[152:153] op_sel_hi:[1,0]
	v_pk_mul_f32 v[128:129], v[128:129], v[152:153] op_sel_hi:[1,0]
	v_pk_mul_f32 v[122:123], v[122:123], v[152:153] op_sel_hi:[1,0]
	v_pk_mul_f32 v[124:125], v[124:125], v[152:153] op_sel_hi:[1,0]
	ds_swizzle_b32 v114, v126 offset:0x401f
	ds_swizzle_b32 v115, v127 offset:0x401f
	ds_swizzle_b32 v116, v128 offset:0x401f
	ds_swizzle_b32 v117, v129 offset:0x401f
	s_waitcnt vmcnt(4)
	v_xor_b32_e32 v162, v201, v162
	v_xor_b32_e32 v163, v201, v163
	v_xor_b32_e32 v164, v201, v164
	v_xor_b32_e32 v165, v201, v165
	v_xor_b32_e32 v166, v201, v166
	v_xor_b32_e32 v167, v201, v167
	v_xor_b32_e32 v168, v201, v168
	v_xor_b32_e32 v169, v201, v169
	s_waitcnt lgkmcnt(0)
	v_mul_f32_e32 v114, v162, v114
	v_fmac_f32_e32 v114, v126, v154
	v_cndmask_b32_e64 v126, v126, v114, s[38:39]
	v_mul_f32_e32 v115, v163, v115
	v_fmac_f32_e32 v115, v127, v155
	v_cndmask_b32_e64 v127, v127, v115, s[38:39]
	v_mul_f32_e32 v116, v164, v116
	v_fmac_f32_e32 v116, v128, v156
	v_cndmask_b32_e64 v128, v128, v116, s[38:39]
	v_mul_f32_e32 v117, v165, v117
	v_fmac_f32_e32 v117, v129, v157
	v_cndmask_b32_e64 v129, v129, v117, s[38:39]
	ds_swizzle_b32 v114, v122 offset:0x401f
	ds_swizzle_b32 v115, v123 offset:0x401f
	ds_swizzle_b32 v116, v124 offset:0x401f
	ds_swizzle_b32 v117, v125 offset:0x401f
	s_waitcnt lgkmcnt(0)
	v_mul_f32_e32 v114, v166, v114
	v_fmac_f32_e32 v114, v122, v158
	v_cndmask_b32_e64 v122, v122, v114, s[38:39]
	v_mul_f32_e32 v115, v167, v115
	v_fmac_f32_e32 v115, v123, v159
	v_cndmask_b32_e64 v123, v123, v115, s[38:39]
	v_mul_f32_e32 v116, v168, v116
	v_fmac_f32_e32 v116, v124, v160
	v_cndmask_b32_e64 v124, v124, v116, s[38:39]
	v_mul_f32_e32 v117, v169, v117
	v_fmac_f32_e32 v117, v125, v161
	v_cndmask_b32_e64 v125, v125, v117, s[38:39]
	v_pk_mul_f32 v[126:127], v[126:127], s[30:31] op_sel_hi:[1,0]
	v_pk_mul_f32 v[128:129], v[128:129], s[30:31] op_sel_hi:[1,0]
	v_pk_mul_f32 v[122:123], v[122:123], s[30:31] op_sel_hi:[1,0]
	v_pk_mul_f32 v[124:125], v[124:125], s[30:31] op_sel_hi:[1,0]
	v_cvt_pk_bf16_f32 v126, v126, v127
	v_cvt_pk_bf16_f32 v127, v128, v129
	v_cvt_pk_bf16_f32 v128, v122, v123
	v_cvt_pk_bf16_f32 v129, v124, v125
	ds_write_b128 v178, v[126:129]
	ds_write_b128 v178, v[118:121] offset:64
	ds_read_b128 v[122:125], v180
	ds_read_b128 v[114:117], v180 offset:1152
	s_add_i32 s44, s19, 32
	s_and_b32 s44, s44, 0xfff
	v_or_b32_e32 v0, s44, v141
	v_lshlrev_b32_e32 v0, 6, v0
	s_mov_b64 s[44:45], exec
	s_and_b64 exec, exec, s[38:39]
	global_load_dwordx4 v[154:157], v0, s[62:63]
	global_load_dwordx4 v[158:161], v0, s[62:63] offset:16
	global_load_dwordx4 v[162:165], v0, s[62:63] offset:32
	global_load_dwordx4 v[166:169], v0, s[62:63] offset:48
	s_mov_b64 exec, s[44:45]
	v_pk_mul_f32 v[102:103], v[102:103], v[152:153] op_sel:[0,1]
	v_pk_mul_f32 v[104:105], v[104:105], v[152:153] op_sel:[0,1]
	v_pk_mul_f32 v[98:99], v[98:99], v[152:153] op_sel:[0,1]
	v_pk_mul_f32 v[100:101], v[100:101], v[152:153] op_sel:[0,1]
	v_pk_mul_f32 v[102:103], v[102:103], s[30:31] op_sel_hi:[1,0]
	v_pk_mul_f32 v[104:105], v[104:105], s[30:31] op_sel_hi:[1,0]
	v_pk_mul_f32 v[98:99], v[98:99], s[30:31] op_sel_hi:[1,0]
	v_pk_mul_f32 v[100:101], v[100:101], s[30:31] op_sel_hi:[1,0]
	v_cvt_pk_bf16_f32 v102, v102, v103
	v_cvt_pk_bf16_f32 v103, v104, v105
	v_cvt_pk_bf16_f32 v104, v98, v99
	v_cvt_pk_bf16_f32 v105, v100, v101
	v_pk_mul_f32 v[110:111], v[110:111], v[152:153] op_sel:[0,1]
	v_pk_mul_f32 v[112:113], v[112:113], v[152:153] op_sel:[0,1]
	v_pk_mul_f32 v[106:107], v[106:107], v[152:153] op_sel:[0,1]
	v_pk_mul_f32 v[108:109], v[108:109], v[152:153] op_sel:[0,1]
	ds_swizzle_b32 v98, v110 offset:0x401f
	ds_swizzle_b32 v99, v111 offset:0x401f
	ds_swizzle_b32 v100, v112 offset:0x401f
	ds_swizzle_b32 v101, v113 offset:0x401f
	s_waitcnt vmcnt(4)
	v_xor_b32_e32 v226, v201, v226
	v_xor_b32_e32 v227, v201, v227
	v_xor_b32_e32 v228, v201, v228
	v_xor_b32_e32 v229, v201, v229
	v_xor_b32_e32 v230, v201, v230
	v_xor_b32_e32 v231, v201, v231
	v_xor_b32_e32 v232, v201, v232
	v_xor_b32_e32 v233, v201, v233
	s_waitcnt lgkmcnt(0)
;     __device__ __forceinline__ void operator()(const f32x4 (&acc)[2][2][4][2], const Unit& u, int wr, int wc, int fr, int fq, PG8_LAS float* stash, int par, PG8_LAS unsigned char* stg, const Unit& un) const {
;     ...
;                     for (int i = 0; i < 4; ++i) { v[i] = acc[ai][bj][m][0][i] * rs; v[4 + i] = acc[ai][bj][m][1][i] * rs; }
;                     if (kind <= 1 && bj == 0) {
;                         const f32x4 c0 = *(const f32x4*)(cs + pos * 16), c1 = *(const f32x4*)(cs + pos * 16 + 4), s0 = *(const f32x4*)(cs + pos * 16 + 8), s1 = *(const f32x4*)(cs + pos * 16 + 12);
; #pragma unroll
;                         for (int i = 0; i < 8; ++i) {
;                             const float c = i < 4 ? c0[i & 3] : c1[i & 3], s = i < 4 ? s0[i & 3] : s1[i & 3];
;                             const float pr = peer_x16(v[i], fq);
;                             const float r = (fq == 0) ? (v[i] * c - pr * s) : (v[i] * c + pr * s);
;                             v[i] = (fq < 2) ? r : v[i];
;                         }
;                     }
;                     if (kind == 0) {
; #pragma unroll
;                         for (int i = 0; i < 8; ++i) v[i] *= C2Q;
;                     }
;                     { u32x4 w; w.x = cvt_pk_bf16(v[0], v[1]); w.y = cvt_pk_bf16(v[2], v[3]); w.z = cvt_pk_bf16(v[4], v[5]); w.w = cvt_pk_bf16(v[6], v[7]);
;                       *(PG8_LAS u32x4*)(stg + fr * 144 + fq * 16 + bj * 64) = w; }
;                 }
;                 {
;                     int kind;
;                     if (odd) kind = (u.pn < 6) ? 0 : (u.pn == 6 ? 1 : 2);
;                     else     kind = (u.pn < 2) ? 0 : (u.pn == 2 ? (wc < 2 ? 1 : 2) : 3);
; #pragma unroll
;                     for (int i = 0; i < 2; ++i) { const int c = fq * 16 + fr + 64 * i, rr = c >> 3, pc = c & 7;
;                         const u32x4 w = *(const PG8_LAS u32x4*)(stg + rr * 144 + pc * 16);
;                         const int rowc = row - fr + rr, posc = rowc & 4095;
;                         if (kind == 1 || kind == 2) {
;                             bf16_t* dst = (kind == 1) ? kd : vt;
;                             if (odd) *(u32x4*)(dst + (size_t)(b * 4 + wc) * (4096 * 64) + (size_t)((posc & 15) * 256 + (posc >> 4)) * 64 + pc * 8) = w;
;                             else     *(u32x4*)(dst + (size_t)(b * 2 + (wc & 1)) * (4096 * 64) + (size_t)posc * 64 + pc * 8) = w;
	v_mul_f32_e32 v98, v226, v98
	v_fmac_f32_e32 v98, v110, v218
	v_cndmask_b32_e64 v110, v110, v98, s[38:39]
	v_mul_f32_e32 v99, v227, v99
	v_fmac_f32_e32 v99, v111, v219
	v_cndmask_b32_e64 v111, v111, v99, s[38:39]
	v_mul_f32_e32 v100, v228, v100
	v_fmac_f32_e32 v100, v112, v220
	v_cndmask_b32_e64 v112, v112, v100, s[38:39]
	v_mul_f32_e32 v101, v229, v101
	v_fmac_f32_e32 v101, v113, v221
	v_cndmask_b32_e64 v113, v113, v101, s[38:39]
	ds_swizzle_b32 v98, v106 offset:0x401f
	ds_swizzle_b32 v99, v107 offset:0x401f
	ds_swizzle_b32 v100, v108 offset:0x401f
	ds_swizzle_b32 v101, v109 offset:0x401f
	s_waitcnt lgkmcnt(0)
	v_mul_f32_e32 v98, v230, v98
	v_fmac_f32_e32 v98, v106, v222
	v_cndmask_b32_e64 v106, v106, v98, s[38:39]
	v_mul_f32_e32 v99, v231, v99
	v_fmac_f32_e32 v99, v107, v223
	v_cndmask_b32_e64 v107, v107, v99, s[38:39]
	v_mul_f32_e32 v100, v232, v100
	v_fmac_f32_e32 v100, v108, v224
	v_cndmask_b32_e64 v108, v108, v100, s[38:39]
	v_mul_f32_e32 v101, v233, v101
	v_fmac_f32_e32 v101, v109, v225
	v_cndmask_b32_e64 v109, v109, v101, s[38:39]
	v_pk_mul_f32 v[110:111], v[110:111], s[30:31] op_sel_hi:[1,0]
	v_pk_mul_f32 v[112:113], v[112:113], s[30:31] op_sel_hi:[1,0]
	v_pk_mul_f32 v[106:107], v[106:107], s[30:31] op_sel_hi:[1,0]
	v_pk_mul_f32 v[108:109], v[108:109], s[30:31] op_sel_hi:[1,0]
	v_cvt_pk_bf16_f32 v110, v110, v111
	v_cvt_pk_bf16_f32 v111, v112, v113
	v_cvt_pk_bf16_f32 v112, v106, v107
	v_cvt_pk_bf16_f32 v113, v108, v109
	s_mov_b32 s100, s98
	s_mov_b32 s101, s99
	global_store_dwordx4 v200, v[122:125], s[100:101] nt
	s_add_u32 s100, s100, s67
	s_addc_u32 s101, s101, 0
	global_store_dwordx4 v200, v[114:117], s[100:101] nt
	ds_write_b128 v178, v[110:113]
	ds_write_b128 v178, v[102:105] offset:64
	ds_read_b128 v[106:109], v180
	ds_read_b128 v[98:101], v180 offset:1152
	s_add_i32 s44, s19, 48
	s_and_b32 s44, s44, 0xfff
	v_or_b32_e32 v0, s44, v141
	v_lshlrev_b32_e32 v0, 6, v0
	s_mov_b64 s[44:45], exec
	s_and_b64 exec, exec, s[38:39]
	global_load_dwordx4 v[218:221], v0, s[62:63]
	global_load_dwordx4 v[222:225], v0, s[62:63] offset:16
	global_load_dwordx4 v[226:229], v0, s[62:63] offset:32
	global_load_dwordx4 v[230:233], v0, s[62:63] offset:48
	s_mov_b64 exec, s[44:45]
	v_pk_mul_f32 v[86:87], v[86:87], v[150:151] op_sel_hi:[1,0]
	v_pk_mul_f32 v[88:89], v[88:89], v[150:151] op_sel_hi:[1,0]
	v_pk_mul_f32 v[82:83], v[82:83], v[150:151] op_sel_hi:[1,0]
	v_pk_mul_f32 v[84:85], v[84:85], v[150:151] op_sel_hi:[1,0]
	v_pk_mul_f32 v[86:87], v[86:87], s[30:31] op_sel_hi:[1,0]
	v_pk_mul_f32 v[88:89], v[88:89], s[30:31] op_sel_hi:[1,0]
	v_pk_mul_f32 v[82:83], v[82:83], s[30:31] op_sel_hi:[1,0]
	v_pk_mul_f32 v[84:85], v[84:85], s[30:31] op_sel_hi:[1,0]
	v_cvt_pk_bf16_f32 v86, v86, v87
	v_cvt_pk_bf16_f32 v87, v88, v89
	v_cvt_pk_bf16_f32 v88, v82, v83
	v_cvt_pk_bf16_f32 v89, v84, v85
	v_pk_mul_f32 v[94:95], v[94:95], v[150:151] op_sel_hi:[1,0]
	v_pk_mul_f32 v[96:97], v[96:97], v[150:151] op_sel_hi:[1,0]
	v_pk_mul_f32 v[90:91], v[90:91], v[150:151] op_sel_hi:[1,0]
	v_pk_mul_f32 v[92:93], v[92:93], v[150:151] op_sel_hi:[1,0]
	ds_swizzle_b32 v82, v94 offset:0x401f
	ds_swizzle_b32 v83, v95 offset:0x401f
	ds_swizzle_b32 v84, v96 offset:0x401f
	ds_swizzle_b32 v85, v97 offset:0x401f
	s_waitcnt vmcnt(6)
	v_xor_b32_e32 v162, v201, v162
	v_xor_b32_e32 v163, v201, v163
	v_xor_b32_e32 v164, v201, v164
	v_xor_b32_e32 v165, v201, v165
	v_xor_b32_e32 v166, v201, v166
	v_xor_b32_e32 v167, v201, v167
	v_xor_b32_e32 v168, v201, v168
	v_xor_b32_e32 v169, v201, v169
	s_waitcnt lgkmcnt(0)
	v_mul_f32_e32 v82, v162, v82
	v_fmac_f32_e32 v82, v94, v154
	v_cndmask_b32_e64 v94, v94, v82, s[38:39]
	v_mul_f32_e32 v83, v163, v83
	v_fmac_f32_e32 v83, v95, v155
	v_cndmask_b32_e64 v95, v95, v83, s[38:39]
	v_mul_f32_e32 v84, v164, v84
	v_fmac_f32_e32 v84, v96, v156
	v_cndmask_b32_e64 v96, v96, v84, s[38:39]
	v_mul_f32_e32 v85, v165, v85
	v_fmac_f32_e32 v85, v97, v157
	v_cndmask_b32_e64 v97, v97, v85, s[38:39]
	ds_swizzle_b32 v82, v90 offset:0x401f
	ds_swizzle_b32 v83, v91 offset:0x401f
	ds_swizzle_b32 v84, v92 offset:0x401f
	ds_swizzle_b32 v85, v93 offset:0x401f
	s_waitcnt lgkmcnt(0)
	v_mul_f32_e32 v82, v166, v82
	v_fmac_f32_e32 v82, v90, v158
	v_cndmask_b32_e64 v90, v90, v82, s[38:39]
	v_mul_f32_e32 v83, v167, v83
	v_fmac_f32_e32 v83, v91, v159
	v_cndmask_b32_e64 v91, v91, v83, s[38:39]
	v_mul_f32_e32 v84, v168, v84
	v_fmac_f32_e32 v84, v92, v160
	v_cndmask_b32_e64 v92, v92, v84, s[38:39]
	v_mul_f32_e32 v85, v169, v85
	v_fmac_f32_e32 v85, v93, v161
	v_cndmask_b32_e64 v93, v93, v85, s[38:39]
	v_pk_mul_f32 v[94:95], v[94:95], s[30:31] op_sel_hi:[1,0]
	v_pk_mul_f32 v[96:97], v[96:97], s[30:31] op_sel_hi:[1,0]
	v_pk_mul_f32 v[90:91], v[90:91], s[30:31] op_sel_hi:[1,0]
	v_pk_mul_f32 v[92:93], v[92:93], s[30:31] op_sel_hi:[1,0]
	v_cvt_pk_bf16_f32 v94, v94, v95
	v_cvt_pk_bf16_f32 v95, v96, v97
	v_cvt_pk_bf16_f32 v96, v90, v91
	v_cvt_pk_bf16_f32 v97, v92, v93
	s_mul_i32 s44, s66, 16
	s_add_u32 s100, s98, s44
	s_addc_u32 s101, s99, 0
	global_store_dwordx4 v200, v[106:109], s[100:101] nt
	s_add_u32 s100, s100, s67
	s_addc_u32 s101, s101, 0
	global_store_dwordx4 v200, v[98:101], s[100:101] nt
	ds_write_b128 v178, v[94:97]
	ds_write_b128 v178, v[86:89] offset:64
	ds_read_b128 v[90:93], v180
	ds_read_b128 v[82:85], v180 offset:1152
	s_add_i32 s44, s19, 128
	s_and_b32 s44, s44, 0xfff
	v_or_b32_e32 v0, s44, v141
	v_lshlrev_b32_e32 v0, 6, v0
	s_mov_b64 s[44:45], exec
	s_and_b64 exec, exec, s[38:39]
	global_load_dwordx4 v[154:157], v0, s[62:63]
	global_load_dwordx4 v[158:161], v0, s[62:63] offset:16
	global_load_dwordx4 v[162:165], v0, s[62:63] offset:32
	global_load_dwordx4 v[166:169], v0, s[62:63] offset:48
	s_mov_b64 exec, s[44:45]
	v_pk_mul_f32 v[70:71], v[70:71], v[150:151] op_sel:[0,1]
	v_pk_mul_f32 v[72:73], v[72:73], v[150:151] op_sel:[0,1]
	v_pk_mul_f32 v[66:67], v[66:67], v[150:151] op_sel:[0,1]
	v_pk_mul_f32 v[68:69], v[68:69], v[150:151] op_sel:[0,1]
	v_pk_mul_f32 v[70:71], v[70:71], s[30:31] op_sel_hi:[1,0]
	v_pk_mul_f32 v[72:73], v[72:73], s[30:31] op_sel_hi:[1,0]
	v_pk_mul_f32 v[66:67], v[66:67], s[30:31] op_sel_hi:[1,0]
	v_pk_mul_f32 v[68:69], v[68:69], s[30:31] op_sel_hi:[1,0]
	v_cvt_pk_bf16_f32 v70, v70, v71
	v_cvt_pk_bf16_f32 v71, v72, v73
	v_cvt_pk_bf16_f32 v72, v66, v67
	v_cvt_pk_bf16_f32 v73, v68, v69
	v_pk_mul_f32 v[78:79], v[78:79], v[150:151] op_sel:[0,1]
	v_pk_mul_f32 v[80:81], v[80:81], v[150:151] op_sel:[0,1]
	v_pk_mul_f32 v[74:75], v[74:75], v[150:151] op_sel:[0,1]
	v_pk_mul_f32 v[76:77], v[76:77], v[150:151] op_sel:[0,1]
	ds_swizzle_b32 v66, v78 offset:0x401f
	ds_swizzle_b32 v67, v79 offset:0x401f
	ds_swizzle_b32 v68, v80 offset:0x401f
	ds_swizzle_b32 v69, v81 offset:0x401f
	s_waitcnt vmcnt(6)
;     __device__ __forceinline__ void operator()(const f32x4 (&acc)[2][2][4][2], const Unit& u, int wr, int wc, int fr, int fq, PG8_LAS float* stash, int par, PG8_LAS unsigned char* stg, const Unit& un) const {
;     ...
;                     for (int i = 0; i < 4; ++i) { v[i] = acc[ai][bj][m][0][i] * rs; v[4 + i] = acc[ai][bj][m][1][i] * rs; }
;                     if (kind <= 1 && bj == 0) {
;                         const f32x4 c0 = *(const f32x4*)(cs + pos * 16), c1 = *(const f32x4*)(cs + pos * 16 + 4), s0 = *(const f32x4*)(cs + pos * 16 + 8), s1 = *(const f32x4*)(cs + pos * 16 + 12);
; #pragma unroll
;                         for (int i = 0; i < 8; ++i) {
;                             const float c = i < 4 ? c0[i & 3] : c1[i & 3], s = i < 4 ? s0[i & 3] : s1[i & 3];
;                             const float pr = peer_x16(v[i], fq);
;                             const float r = (fq == 0) ? (v[i] * c - pr * s) : (v[i] * c + pr * s);
;                             v[i] = (fq < 2) ? r : v[i];
;                         }
;                     }
;                     if (kind == 0) {
; #pragma unroll
;                         for (int i = 0; i < 8; ++i) v[i] *= C2Q;
;                     }
;                     { u32x4 w; w.x = cvt_pk_bf16(v[0], v[1]); w.y = cvt_pk_bf16(v[2], v[3]); w.z = cvt_pk_bf16(v[4], v[5]); w.w = cvt_pk_bf16(v[6], v[7]);
;                       *(PG8_LAS u32x4*)(stg + fr * 144 + fq * 16 + bj * 64) = w; }
;                 }
;                 {
;                     int kind;
;                     if (odd) kind = (u.pn < 6) ? 0 : (u.pn == 6 ? 1 : 2);
;                     else     kind = (u.pn < 2) ? 0 : (u.pn == 2 ? (wc < 2 ? 1 : 2) : 3);
; #pragma unroll
;                     for (int i = 0; i < 2; ++i) { const int c = fq * 16 + fr + 64 * i, rr = c >> 3, pc = c & 7;
;                         const u32x4 w = *(const PG8_LAS u32x4*)(stg + rr * 144 + pc * 16);
;                         const int rowc = row - fr + rr, posc = rowc & 4095;
;                         if (kind == 1 || kind == 2) {
;                             bf16_t* dst = (kind == 1) ? kd : vt;
;                             if (odd) *(u32x4*)(dst + (size_t)(b * 4 + wc) * (4096 * 64) + (size_t)((posc & 15) * 256 + (posc >> 4)) * 64 + pc * 8) = w;
;                             else     *(u32x4*)(dst + (size_t)(b * 2 + (wc & 1)) * (4096 * 64) + (size_t)posc * 64 + pc * 8) = w;
	v_xor_b32_e32 v226, v201, v226
	v_xor_b32_e32 v227, v201, v227
	v_xor_b32_e32 v228, v201, v228
	v_xor_b32_e32 v229, v201, v229
	v_xor_b32_e32 v230, v201, v230
	v_xor_b32_e32 v231, v201, v231
	v_xor_b32_e32 v232, v201, v232
	v_xor_b32_e32 v233, v201, v233
	s_waitcnt lgkmcnt(0)
	v_mul_f32_e32 v66, v226, v66
	v_fmac_f32_e32 v66, v78, v218
	v_cndmask_b32_e64 v78, v78, v66, s[38:39]
	v_mul_f32_e32 v67, v227, v67
	v_fmac_f32_e32 v67, v79, v219
	v_cndmask_b32_e64 v79, v79, v67, s[38:39]
	v_mul_f32_e32 v68, v228, v68
	v_fmac_f32_e32 v68, v80, v220
	v_cndmask_b32_e64 v80, v80, v68, s[38:39]
	v_mul_f32_e32 v69, v229, v69
	v_fmac_f32_e32 v69, v81, v221
	v_cndmask_b32_e64 v81, v81, v69, s[38:39]
	ds_swizzle_b32 v66, v74 offset:0x401f
	ds_swizzle_b32 v67, v75 offset:0x401f
	ds_swizzle_b32 v68, v76 offset:0x401f
	ds_swizzle_b32 v69, v77 offset:0x401f
	s_waitcnt lgkmcnt(0)
	v_mul_f32_e32 v66, v230, v66
	v_fmac_f32_e32 v66, v74, v222
	v_cndmask_b32_e64 v74, v74, v66, s[38:39]
	v_mul_f32_e32 v67, v231, v67
	v_fmac_f32_e32 v67, v75, v223
	v_cndmask_b32_e64 v75, v75, v67, s[38:39]
	v_mul_f32_e32 v68, v232, v68
	v_fmac_f32_e32 v68, v76, v224
	v_cndmask_b32_e64 v76, v76, v68, s[38:39]
	v_mul_f32_e32 v69, v233, v69
	v_fmac_f32_e32 v69, v77, v225
	v_cndmask_b32_e64 v77, v77, v69, s[38:39]
	v_pk_mul_f32 v[78:79], v[78:79], s[30:31] op_sel_hi:[1,0]
	v_pk_mul_f32 v[80:81], v[80:81], s[30:31] op_sel_hi:[1,0]
	v_pk_mul_f32 v[74:75], v[74:75], s[30:31] op_sel_hi:[1,0]
	v_pk_mul_f32 v[76:77], v[76:77], s[30:31] op_sel_hi:[1,0]
	v_cvt_pk_bf16_f32 v78, v78, v79
	v_cvt_pk_bf16_f32 v79, v80, v81
	v_cvt_pk_bf16_f32 v80, v74, v75
	v_cvt_pk_bf16_f32 v81, v76, v77
	s_mul_i32 s44, s66, 32
	s_add_u32 s100, s98, s44
	s_addc_u32 s101, s99, 0
	global_store_dwordx4 v200, v[90:93], s[100:101] nt
	s_add_u32 s100, s100, s67
	s_addc_u32 s101, s101, 0
	global_store_dwordx4 v200, v[82:85], s[100:101] nt
	ds_write_b128 v178, v[78:81]
	ds_write_b128 v178, v[70:73] offset:64
	ds_read_b128 v[74:77], v180
	ds_read_b128 v[66:69], v180 offset:1152
	s_add_i32 s44, s19, 144
	s_and_b32 s44, s44, 0xfff
	v_or_b32_e32 v0, s44, v141
	v_lshlrev_b32_e32 v0, 6, v0
	s_mov_b64 s[44:45], exec
	s_and_b64 exec, exec, s[38:39]
	global_load_dwordx4 v[218:221], v0, s[62:63]
	global_load_dwordx4 v[222:225], v0, s[62:63] offset:16
	global_load_dwordx4 v[226:229], v0, s[62:63] offset:32
	global_load_dwordx4 v[230:233], v0, s[62:63] offset:48
	s_mov_b64 exec, s[44:45]
	v_pk_mul_f32 v[54:55], v[54:55], v[148:149] op_sel_hi:[1,0]
	v_pk_mul_f32 v[56:57], v[56:57], v[148:149] op_sel_hi:[1,0]
	v_pk_mul_f32 v[50:51], v[50:51], v[148:149] op_sel_hi:[1,0]
	v_pk_mul_f32 v[52:53], v[52:53], v[148:149] op_sel_hi:[1,0]
	v_pk_mul_f32 v[54:55], v[54:55], s[30:31] op_sel_hi:[1,0]
	v_pk_mul_f32 v[56:57], v[56:57], s[30:31] op_sel_hi:[1,0]
	v_pk_mul_f32 v[50:51], v[50:51], s[30:31] op_sel_hi:[1,0]
	v_pk_mul_f32 v[52:53], v[52:53], s[30:31] op_sel_hi:[1,0]
	v_cvt_pk_bf16_f32 v54, v54, v55
	v_cvt_pk_bf16_f32 v55, v56, v57
	v_cvt_pk_bf16_f32 v56, v50, v51
	v_cvt_pk_bf16_f32 v57, v52, v53
	v_pk_mul_f32 v[62:63], v[62:63], v[148:149] op_sel_hi:[1,0]
	v_pk_mul_f32 v[64:65], v[64:65], v[148:149] op_sel_hi:[1,0]
	v_pk_mul_f32 v[58:59], v[58:59], v[148:149] op_sel_hi:[1,0]
	v_pk_mul_f32 v[60:61], v[60:61], v[148:149] op_sel_hi:[1,0]
	ds_swizzle_b32 v50, v62 offset:0x401f
	ds_swizzle_b32 v51, v63 offset:0x401f
	ds_swizzle_b32 v52, v64 offset:0x401f
	ds_swizzle_b32 v53, v65 offset:0x401f
	s_waitcnt vmcnt(6)
	v_xor_b32_e32 v162, v201, v162
	v_xor_b32_e32 v163, v201, v163
	v_xor_b32_e32 v164, v201, v164
	v_xor_b32_e32 v165, v201, v165
	v_xor_b32_e32 v166, v201, v166
	v_xor_b32_e32 v167, v201, v167
	v_xor_b32_e32 v168, v201, v168
	v_xor_b32_e32 v169, v201, v169
	s_waitcnt lgkmcnt(0)
	v_mul_f32_e32 v50, v162, v50
	v_fmac_f32_e32 v50, v62, v154
	v_cndmask_b32_e64 v62, v62, v50, s[38:39]
	v_mul_f32_e32 v51, v163, v51
	v_fmac_f32_e32 v51, v63, v155
	v_cndmask_b32_e64 v63, v63, v51, s[38:39]
	v_mul_f32_e32 v52, v164, v52
	v_fmac_f32_e32 v52, v64, v156
	v_cndmask_b32_e64 v64, v64, v52, s[38:39]
	v_mul_f32_e32 v53, v165, v53
	v_fmac_f32_e32 v53, v65, v157
	v_cndmask_b32_e64 v65, v65, v53, s[38:39]
	ds_swizzle_b32 v50, v58 offset:0x401f
	ds_swizzle_b32 v51, v59 offset:0x401f
	ds_swizzle_b32 v52, v60 offset:0x401f
	ds_swizzle_b32 v53, v61 offset:0x401f
	s_waitcnt lgkmcnt(0)
	v_mul_f32_e32 v50, v166, v50
	v_fmac_f32_e32 v50, v58, v158
	v_cndmask_b32_e64 v58, v58, v50, s[38:39]
	v_mul_f32_e32 v51, v167, v51
	v_fmac_f32_e32 v51, v59, v159
	v_cndmask_b32_e64 v59, v59, v51, s[38:39]
	v_mul_f32_e32 v52, v168, v52
	v_fmac_f32_e32 v52, v60, v160
	v_cndmask_b32_e64 v60, v60, v52, s[38:39]
	v_mul_f32_e32 v53, v169, v53
	v_fmac_f32_e32 v53, v61, v161
	v_cndmask_b32_e64 v61, v61, v53, s[38:39]
	v_pk_mul_f32 v[62:63], v[62:63], s[30:31] op_sel_hi:[1,0]
	v_pk_mul_f32 v[64:65], v[64:65], s[30:31] op_sel_hi:[1,0]
	v_pk_mul_f32 v[58:59], v[58:59], s[30:31] op_sel_hi:[1,0]
	v_pk_mul_f32 v[60:61], v[60:61], s[30:31] op_sel_hi:[1,0]
	v_cvt_pk_bf16_f32 v62, v62, v63
	v_cvt_pk_bf16_f32 v63, v64, v65
	v_cvt_pk_bf16_f32 v64, v58, v59
	v_cvt_pk_bf16_f32 v65, v60, v61
	s_mul_i32 s44, s66, 48
	s_add_u32 s100, s98, s44
	s_addc_u32 s101, s99, 0
	global_store_dwordx4 v200, v[74:77], s[100:101] nt
	s_add_u32 s100, s100, s67
	s_addc_u32 s101, s101, 0
	global_store_dwordx4 v200, v[66:69], s[100:101] nt
	ds_write_b128 v178, v[62:65]
	ds_write_b128 v178, v[54:57] offset:64
	ds_read_b128 v[58:61], v180
	ds_read_b128 v[50:53], v180 offset:1152
	s_add_i32 s44, s19, 160
	s_and_b32 s44, s44, 0xfff
	v_or_b32_e32 v0, s44, v141
	v_lshlrev_b32_e32 v0, 6, v0
	s_mov_b64 s[44:45], exec
	s_and_b64 exec, exec, s[38:39]
	global_load_dwordx4 v[154:157], v0, s[62:63]
	global_load_dwordx4 v[158:161], v0, s[62:63] offset:16
	global_load_dwordx4 v[162:165], v0, s[62:63] offset:32
	global_load_dwordx4 v[166:169], v0, s[62:63] offset:48
	s_mov_b64 exec, s[44:45]
	v_pk_mul_f32 v[38:39], v[38:39], v[148:149] op_sel:[0,1]
	v_pk_mul_f32 v[40:41], v[40:41], v[148:149] op_sel:[0,1]
	v_pk_mul_f32 v[34:35], v[34:35], v[148:149] op_sel:[0,1]
	v_pk_mul_f32 v[36:37], v[36:37], v[148:149] op_sel:[0,1]
	v_pk_mul_f32 v[38:39], v[38:39], s[30:31] op_sel_hi:[1,0]
	v_pk_mul_f32 v[40:41], v[40:41], s[30:31] op_sel_hi:[1,0]
	v_pk_mul_f32 v[34:35], v[34:35], s[30:31] op_sel_hi:[1,0]
	v_pk_mul_f32 v[36:37], v[36:37], s[30:31] op_sel_hi:[1,0]
	v_cvt_pk_bf16_f32 v38, v38, v39
	v_cvt_pk_bf16_f32 v39, v40, v41
	v_cvt_pk_bf16_f32 v40, v34, v35
	v_cvt_pk_bf16_f32 v41, v36, v37
	v_pk_mul_f32 v[46:47], v[46:47], v[148:149] op_sel:[0,1]
	v_pk_mul_f32 v[48:49], v[48:49], v[148:149] op_sel:[0,1]
	v_pk_mul_f32 v[42:43], v[42:43], v[148:149] op_sel:[0,1]
	v_pk_mul_f32 v[44:45], v[44:45], v[148:149] op_sel:[0,1]
	ds_swizzle_b32 v34, v46 offset:0x401f
	ds_swizzle_b32 v35, v47 offset:0x401f
	ds_swizzle_b32 v36, v48 offset:0x401f
	ds_swizzle_b32 v37, v49 offset:0x401f
	s_waitcnt vmcnt(6)
;     __device__ __forceinline__ void operator()(const f32x4 (&acc)[2][2][4][2], const Unit& u, int wr, int wc, int fr, int fq, PG8_LAS float* stash, int par, PG8_LAS unsigned char* stg, const Unit& un) const {
;     ...
;                     for (int i = 0; i < 4; ++i) { v[i] = acc[ai][bj][m][0][i] * rs; v[4 + i] = acc[ai][bj][m][1][i] * rs; }
;                     if (kind <= 1 && bj == 0) {
;                         const f32x4 c0 = *(const f32x4*)(cs + pos * 16), c1 = *(const f32x4*)(cs + pos * 16 + 4), s0 = *(const f32x4*)(cs + pos * 16 + 8), s1 = *(const f32x4*)(cs + pos * 16 + 12);
; #pragma unroll
;                         for (int i = 0; i < 8; ++i) {
;                             const float c = i < 4 ? c0[i & 3] : c1[i & 3], s = i < 4 ? s0[i & 3] : s1[i & 3];
;                             const float pr = peer_x16(v[i], fq);
;                             const float r = (fq == 0) ? (v[i] * c - pr * s) : (v[i] * c + pr * s);
;                             v[i] = (fq < 2) ? r : v[i];
;                         }
;                     }
;                     if (kind == 0) {
; #pragma unroll
;                         for (int i = 0; i < 8; ++i) v[i] *= C2Q;
;                     }
;                     { u32x4 w; w.x = cvt_pk_bf16(v[0], v[1]); w.y = cvt_pk_bf16(v[2], v[3]); w.z = cvt_pk_bf16(v[4], v[5]); w.w = cvt_pk_bf16(v[6], v[7]);
;                       *(PG8_LAS u32x4*)(stg + fr * 144 + fq * 16 + bj * 64) = w; }
;                 }
;                 {
;                     int kind;
;                     if (odd) kind = (u.pn < 6) ? 0 : (u.pn == 6 ? 1 : 2);
;                     else     kind = (u.pn < 2) ? 0 : (u.pn == 2 ? (wc < 2 ? 1 : 2) : 3);
; #pragma unroll
;                     for (int i = 0; i < 2; ++i) { const int c = fq * 16 + fr + 64 * i, rr = c >> 3, pc = c & 7;
;                         const u32x4 w = *(const PG8_LAS u32x4*)(stg + rr * 144 + pc * 16);
;                         const int rowc = row - fr + rr, posc = rowc & 4095;
;                         if (kind == 1 || kind == 2) {
;                             bf16_t* dst = (kind == 1) ? kd : vt;
;                             if (odd) *(u32x4*)(dst + (size_t)(b * 4 + wc) * (4096 * 64) + (size_t)((posc & 15) * 256 + (posc >> 4)) * 64 + pc * 8) = w;
;                             else     *(u32x4*)(dst + (size_t)(b * 2 + (wc & 1)) * (4096 * 64) + (size_t)posc * 64 + pc * 8) = w;
	v_xor_b32_e32 v226, v201, v226
	v_xor_b32_e32 v227, v201, v227
	v_xor_b32_e32 v228, v201, v228
	v_xor_b32_e32 v229, v201, v229
	v_xor_b32_e32 v230, v201, v230
	v_xor_b32_e32 v231, v201, v231
	v_xor_b32_e32 v232, v201, v232
	v_xor_b32_e32 v233, v201, v233
	s_waitcnt lgkmcnt(0)
	v_mul_f32_e32 v34, v226, v34
	v_fmac_f32_e32 v34, v46, v218
	v_cndmask_b32_e64 v46, v46, v34, s[38:39]
	v_mul_f32_e32 v35, v227, v35
	v_fmac_f32_e32 v35, v47, v219
	v_cndmask_b32_e64 v47, v47, v35, s[38:39]
	v_mul_f32_e32 v36, v228, v36
	v_fmac_f32_e32 v36, v48, v220
	v_cndmask_b32_e64 v48, v48, v36, s[38:39]
	v_mul_f32_e32 v37, v229, v37
	v_fmac_f32_e32 v37, v49, v221
	v_cndmask_b32_e64 v49, v49, v37, s[38:39]
	ds_swizzle_b32 v34, v42 offset:0x401f
	ds_swizzle_b32 v35, v43 offset:0x401f
	ds_swizzle_b32 v36, v44 offset:0x401f
	ds_swizzle_b32 v37, v45 offset:0x401f
	s_waitcnt lgkmcnt(0)
	v_mul_f32_e32 v34, v230, v34
	v_fmac_f32_e32 v34, v42, v222
	v_cndmask_b32_e64 v42, v42, v34, s[38:39]
	v_mul_f32_e32 v35, v231, v35
	v_fmac_f32_e32 v35, v43, v223
	v_cndmask_b32_e64 v43, v43, v35, s[38:39]
	v_mul_f32_e32 v36, v232, v36
	v_fmac_f32_e32 v36, v44, v224
	v_cndmask_b32_e64 v44, v44, v36, s[38:39]
	v_mul_f32_e32 v37, v233, v37
	v_fmac_f32_e32 v37, v45, v225
	v_cndmask_b32_e64 v45, v45, v37, s[38:39]
	v_pk_mul_f32 v[46:47], v[46:47], s[30:31] op_sel_hi:[1,0]
	v_pk_mul_f32 v[48:49], v[48:49], s[30:31] op_sel_hi:[1,0]
	v_pk_mul_f32 v[42:43], v[42:43], s[30:31] op_sel_hi:[1,0]
	v_pk_mul_f32 v[44:45], v[44:45], s[30:31] op_sel_hi:[1,0]
	v_cvt_pk_bf16_f32 v46, v46, v47
	v_cvt_pk_bf16_f32 v47, v48, v49
	v_cvt_pk_bf16_f32 v48, v42, v43
	v_cvt_pk_bf16_f32 v49, v44, v45
	s_mul_i32 s44, s66, 128
	s_add_u32 s100, s98, s44
	s_addc_u32 s101, s99, 0
	global_store_dwordx4 v200, v[58:61], s[100:101] nt
	s_add_u32 s100, s100, s67
	s_addc_u32 s101, s101, 0
	global_store_dwordx4 v200, v[50:53], s[100:101] nt
	ds_write_b128 v178, v[46:49]
	ds_write_b128 v178, v[38:41] offset:64
	ds_read_b128 v[42:45], v180
	ds_read_b128 v[34:37], v180 offset:1152
	s_add_i32 s44, s19, 176
	s_and_b32 s44, s44, 0xfff
	v_or_b32_e32 v0, s44, v141
	v_lshlrev_b32_e32 v0, 6, v0
	s_mov_b64 s[44:45], exec
	s_and_b64 exec, exec, s[38:39]
	global_load_dwordx4 v[218:221], v0, s[62:63]
	global_load_dwordx4 v[222:225], v0, s[62:63] offset:16
	global_load_dwordx4 v[226:229], v0, s[62:63] offset:32
	global_load_dwordx4 v[230:233], v0, s[62:63] offset:48
	s_mov_b64 exec, s[44:45]
	v_pk_mul_f32 v[22:23], v[22:23], v[146:147] op_sel_hi:[1,0]
	v_pk_mul_f32 v[24:25], v[24:25], v[146:147] op_sel_hi:[1,0]
	v_pk_mul_f32 v[18:19], v[18:19], v[146:147] op_sel_hi:[1,0]
	v_pk_mul_f32 v[20:21], v[20:21], v[146:147] op_sel_hi:[1,0]
	v_pk_mul_f32 v[22:23], v[22:23], s[30:31] op_sel_hi:[1,0]
	v_pk_mul_f32 v[24:25], v[24:25], s[30:31] op_sel_hi:[1,0]
	v_pk_mul_f32 v[18:19], v[18:19], s[30:31] op_sel_hi:[1,0]
	v_pk_mul_f32 v[20:21], v[20:21], s[30:31] op_sel_hi:[1,0]
	v_cvt_pk_bf16_f32 v22, v22, v23
	v_cvt_pk_bf16_f32 v23, v24, v25
	v_cvt_pk_bf16_f32 v24, v18, v19
	v_cvt_pk_bf16_f32 v25, v20, v21
	v_pk_mul_f32 v[30:31], v[30:31], v[146:147] op_sel_hi:[1,0]
	v_pk_mul_f32 v[32:33], v[32:33], v[146:147] op_sel_hi:[1,0]
	v_pk_mul_f32 v[26:27], v[26:27], v[146:147] op_sel_hi:[1,0]
	v_pk_mul_f32 v[28:29], v[28:29], v[146:147] op_sel_hi:[1,0]
	ds_swizzle_b32 v18, v30 offset:0x401f
	ds_swizzle_b32 v19, v31 offset:0x401f
	ds_swizzle_b32 v20, v32 offset:0x401f
	ds_swizzle_b32 v21, v33 offset:0x401f
	s_waitcnt vmcnt(6)
	v_xor_b32_e32 v162, v201, v162
	v_xor_b32_e32 v163, v201, v163
	v_xor_b32_e32 v164, v201, v164
	v_xor_b32_e32 v165, v201, v165
	v_xor_b32_e32 v166, v201, v166
	v_xor_b32_e32 v167, v201, v167
	v_xor_b32_e32 v168, v201, v168
	v_xor_b32_e32 v169, v201, v169
	s_waitcnt lgkmcnt(0)
	v_mul_f32_e32 v18, v162, v18
	v_fmac_f32_e32 v18, v30, v154
	v_cndmask_b32_e64 v30, v30, v18, s[38:39]
	v_mul_f32_e32 v19, v163, v19
	v_fmac_f32_e32 v19, v31, v155
	v_cndmask_b32_e64 v31, v31, v19, s[38:39]
	v_mul_f32_e32 v20, v164, v20
	v_fmac_f32_e32 v20, v32, v156
	v_cndmask_b32_e64 v32, v32, v20, s[38:39]
	v_mul_f32_e32 v21, v165, v21
	v_fmac_f32_e32 v21, v33, v157
	v_cndmask_b32_e64 v33, v33, v21, s[38:39]
	ds_swizzle_b32 v18, v26 offset:0x401f
	ds_swizzle_b32 v19, v27 offset:0x401f
	ds_swizzle_b32 v20, v28 offset:0x401f
	ds_swizzle_b32 v21, v29 offset:0x401f
	s_waitcnt lgkmcnt(0)
	v_mul_f32_e32 v18, v166, v18
	v_fmac_f32_e32 v18, v26, v158
	v_cndmask_b32_e64 v26, v26, v18, s[38:39]
	v_mul_f32_e32 v19, v167, v19
	v_fmac_f32_e32 v19, v27, v159
	v_cndmask_b32_e64 v27, v27, v19, s[38:39]
	v_mul_f32_e32 v20, v168, v20
	v_fmac_f32_e32 v20, v28, v160
	v_cndmask_b32_e64 v28, v28, v20, s[38:39]
	v_mul_f32_e32 v21, v169, v21
	v_fmac_f32_e32 v21, v29, v161
	v_cndmask_b32_e64 v29, v29, v21, s[38:39]
	v_pk_mul_f32 v[30:31], v[30:31], s[30:31] op_sel_hi:[1,0]
	v_pk_mul_f32 v[32:33], v[32:33], s[30:31] op_sel_hi:[1,0]
	v_pk_mul_f32 v[26:27], v[26:27], s[30:31] op_sel_hi:[1,0]
	v_pk_mul_f32 v[28:29], v[28:29], s[30:31] op_sel_hi:[1,0]
	v_cvt_pk_bf16_f32 v30, v30, v31
	v_cvt_pk_bf16_f32 v31, v32, v33
	v_cvt_pk_bf16_f32 v32, v26, v27
	v_cvt_pk_bf16_f32 v33, v28, v29
	s_mul_i32 s44, s66, 144
	s_add_u32 s100, s98, s44
	s_addc_u32 s101, s99, 0
	global_store_dwordx4 v200, v[42:45], s[100:101] nt
	s_add_u32 s100, s100, s67
	s_addc_u32 s101, s101, 0
	global_store_dwordx4 v200, v[34:37], s[100:101] nt
	ds_write_b128 v178, v[30:33]
	ds_write_b128 v178, v[22:25] offset:64
	ds_read_b128 v[26:29], v180
	ds_read_b128 v[18:21], v180 offset:1152
	v_pk_mul_f32 v[6:7], v[6:7], v[146:147] op_sel:[0,1]
	v_pk_mul_f32 v[8:9], v[8:9], v[146:147] op_sel:[0,1]
	v_pk_mul_f32 v[2:3], v[2:3], v[146:147] op_sel:[0,1]
	v_pk_mul_f32 v[4:5], v[4:5], v[146:147] op_sel:[0,1]
	v_pk_mul_f32 v[6:7], v[6:7], s[30:31] op_sel_hi:[1,0]
	v_pk_mul_f32 v[8:9], v[8:9], s[30:31] op_sel_hi:[1,0]
	v_pk_mul_f32 v[2:3], v[2:3], s[30:31] op_sel_hi:[1,0]
	v_pk_mul_f32 v[4:5], v[4:5], s[30:31] op_sel_hi:[1,0]
	v_cvt_pk_bf16_f32 v6, v6, v7
	v_cvt_pk_bf16_f32 v7, v8, v9
	v_cvt_pk_bf16_f32 v8, v2, v3
	v_cvt_pk_bf16_f32 v9, v4, v5
	v_pk_mul_f32 v[14:15], v[14:15], v[146:147] op_sel:[0,1]
	v_pk_mul_f32 v[16:17], v[16:17], v[146:147] op_sel:[0,1]
	v_pk_mul_f32 v[10:11], v[10:11], v[146:147] op_sel:[0,1]
	v_pk_mul_f32 v[12:13], v[12:13], v[146:147] op_sel:[0,1]
	ds_swizzle_b32 v2, v14 offset:0x401f
	ds_swizzle_b32 v3, v15 offset:0x401f
	ds_swizzle_b32 v4, v16 offset:0x401f
	ds_swizzle_b32 v5, v17 offset:0x401f
	s_waitcnt vmcnt(2)
;     __device__ __forceinline__ void operator()(const f32x4 (&acc)[2][2][4][2], const Unit& u, int wr, int wc, int fr, int fq, PG8_LAS float* stash, int par, PG8_LAS unsigned char* stg, const Unit& un) const {
;     ...
;                     for (int i = 0; i < 4; ++i) { v[i] = acc[ai][bj][m][0][i] * rs; v[4 + i] = acc[ai][bj][m][1][i] * rs; }
;                     if (kind <= 1 && bj == 0) {
;                         const f32x4 c0 = *(const f32x4*)(cs + pos * 16), c1 = *(const f32x4*)(cs + pos * 16 + 4), s0 = *(const f32x4*)(cs + pos * 16 + 8), s1 = *(const f32x4*)(cs + pos * 16 + 12);
; #pragma unroll
;                         for (int i = 0; i < 8; ++i) {
;                             const float c = i < 4 ? c0[i & 3] : c1[i & 3], s = i < 4 ? s0[i & 3] : s1[i & 3];
;                             const float pr = peer_x16(v[i], fq);
;                             const float r = (fq == 0) ? (v[i] * c - pr * s) : (v[i] * c + pr * s);
;                             v[i] = (fq < 2) ? r : v[i];
;                         }
;                     }
;                     if (kind == 0) {
; #pragma unroll
;                         for (int i = 0; i < 8; ++i) v[i] *= C2Q;
;                     }
;                     { u32x4 w; w.x = cvt_pk_bf16(v[0], v[1]); w.y = cvt_pk_bf16(v[2], v[3]); w.z = cvt_pk_bf16(v[4], v[5]); w.w = cvt_pk_bf16(v[6], v[7]);
;                       *(PG8_LAS u32x4*)(stg + fr * 144 + fq * 16 + bj * 64) = w; }
;                 }
;                 {
;                     int kind;
;                     if (odd) kind = (u.pn < 6) ? 0 : (u.pn == 6 ? 1 : 2);
;                     else     kind = (u.pn < 2) ? 0 : (u.pn == 2 ? (wc < 2 ? 1 : 2) : 3);
; #pragma unroll
;                     for (int i = 0; i < 2; ++i) { const int c = fq * 16 + fr + 64 * i, rr = c >> 3, pc = c & 7;
;                         const u32x4 w = *(const PG8_LAS u32x4*)(stg + rr * 144 + pc * 16);
;                         const int rowc = row - fr + rr, posc = rowc & 4095;
;                         if (kind == 1 || kind == 2) {
;                             bf16_t* dst = (kind == 1) ? kd : vt;
;                             if (odd) *(u32x4*)(dst + (size_t)(b * 4 + wc) * (4096 * 64) + (size_t)((posc & 15) * 256 + (posc >> 4)) * 64 + pc * 8) = w;
;                             else     *(u32x4*)(dst + (size_t)(b * 2 + (wc & 1)) * (4096 * 64) + (size_t)posc * 64 + pc * 8) = w;
	v_xor_b32_e32 v226, v201, v226
	v_xor_b32_e32 v227, v201, v227
	v_xor_b32_e32 v228, v201, v228
	v_xor_b32_e32 v229, v201, v229
	v_xor_b32_e32 v230, v201, v230
	v_xor_b32_e32 v231, v201, v231
	v_xor_b32_e32 v232, v201, v232
	v_xor_b32_e32 v233, v201, v233
	s_waitcnt lgkmcnt(0)
	v_mul_f32_e32 v2, v226, v2
	v_fmac_f32_e32 v2, v14, v218
	v_cndmask_b32_e64 v14, v14, v2, s[38:39]
	v_mul_f32_e32 v3, v227, v3
	v_fmac_f32_e32 v3, v15, v219
	v_cndmask_b32_e64 v15, v15, v3, s[38:39]
	v_mul_f32_e32 v4, v228, v4
	v_fmac_f32_e32 v4, v16, v220
	v_cndmask_b32_e64 v16, v16, v4, s[38:39]
	v_mul_f32_e32 v5, v229, v5
	v_fmac_f32_e32 v5, v17, v221
	v_cndmask_b32_e64 v17, v17, v5, s[38:39]
	ds_swizzle_b32 v2, v10 offset:0x401f
	ds_swizzle_b32 v3, v11 offset:0x401f
	ds_swizzle_b32 v4, v12 offset:0x401f
	ds_swizzle_b32 v5, v13 offset:0x401f
	s_waitcnt lgkmcnt(0)
	v_mul_f32_e32 v2, v230, v2
	v_fmac_f32_e32 v2, v10, v222
	v_cndmask_b32_e64 v10, v10, v2, s[38:39]
	v_mul_f32_e32 v3, v231, v3
	v_fmac_f32_e32 v3, v11, v223
	v_cndmask_b32_e64 v11, v11, v3, s[38:39]
	v_mul_f32_e32 v4, v232, v4
	v_fmac_f32_e32 v4, v12, v224
	v_cndmask_b32_e64 v12, v12, v4, s[38:39]
	v_mul_f32_e32 v5, v233, v5
	v_fmac_f32_e32 v5, v13, v225
	v_cndmask_b32_e64 v13, v13, v5, s[38:39]
	v_pk_mul_f32 v[14:15], v[14:15], s[30:31] op_sel_hi:[1,0]
	v_pk_mul_f32 v[16:17], v[16:17], s[30:31] op_sel_hi:[1,0]
	v_pk_mul_f32 v[10:11], v[10:11], s[30:31] op_sel_hi:[1,0]
	v_pk_mul_f32 v[12:13], v[12:13], s[30:31] op_sel_hi:[1,0]
	v_cvt_pk_bf16_f32 v14, v14, v15
	v_cvt_pk_bf16_f32 v15, v16, v17
	v_cvt_pk_bf16_f32 v16, v10, v11
	v_cvt_pk_bf16_f32 v17, v12, v13
	s_mul_i32 s44, s66, 160
	s_add_u32 s100, s98, s44
	s_addc_u32 s101, s99, 0
	global_store_dwordx4 v200, v[26:29], s[100:101] nt
	s_add_u32 s100, s100, s67
	s_addc_u32 s101, s101, 0
	global_store_dwordx4 v200, v[18:21], s[100:101] nt
	ds_write_b128 v178, v[14:17]
	ds_write_b128 v178, v[6:9] offset:64
	ds_read_b128 v[10:13], v180
	ds_read_b128 v[2:5], v180 offset:1152
	s_waitcnt lgkmcnt(0)
	s_mul_i32 s44, s66, 176
	s_add_u32 s100, s98, s44
	s_addc_u32 s101, s99, 0
	global_store_dwordx4 v200, v[10:13], s[100:101] nt
	s_add_u32 s100, s100, s67
	s_addc_u32 s101, s101, 0
	global_store_dwordx4 v200, v[2:5], s[100:101] nt
	s_branch .Lipe_done
.Lipe_K:
	s_add_i32 s44, s19, 0
	s_and_b32 s44, s44, 0xfff
	v_or_b32_e32 v0, s44, v141
	v_lshlrev_b32_e32 v0, 6, v0
	s_mov_b64 s[44:45], exec
	s_and_b64 exec, exec, s[38:39]
	global_load_dwordx4 v[154:157], v0, s[62:63]
	global_load_dwordx4 v[158:161], v0, s[62:63] offset:16
	global_load_dwordx4 v[162:165], v0, s[62:63] offset:32
	global_load_dwordx4 v[166:169], v0, s[62:63] offset:48
	s_mov_b64 exec, s[44:45]
	s_add_i32 s44, s19, 16
	s_and_b32 s44, s44, 0xfff
	v_or_b32_e32 v0, s44, v141
	v_lshlrev_b32_e32 v0, 6, v0
	s_mov_b64 s[44:45], exec
	s_and_b64 exec, exec, s[38:39]
	global_load_dwordx4 v[218:221], v0, s[62:63]
	global_load_dwordx4 v[222:225], v0, s[62:63] offset:16
	global_load_dwordx4 v[226:229], v0, s[62:63] offset:32
	global_load_dwordx4 v[230:233], v0, s[62:63] offset:48
	s_mov_b64 exec, s[44:45]
	v_pk_mul_f32 v[118:119], v[118:119], v[152:153] op_sel_hi:[1,0]
	v_pk_mul_f32 v[120:121], v[120:121], v[152:153] op_sel_hi:[1,0]
	v_pk_mul_f32 v[114:115], v[114:115], v[152:153] op_sel_hi:[1,0]
	v_pk_mul_f32 v[116:117], v[116:117], v[152:153] op_sel_hi:[1,0]
	v_cvt_pk_bf16_f32 v118, v118, v119
	v_cvt_pk_bf16_f32 v119, v120, v121
	v_cvt_pk_bf16_f32 v120, v114, v115
	v_cvt_pk_bf16_f32 v121, v116, v117
	v_pk_mul_f32 v[126:127], v[126:127], v[152:153] op_sel_hi:[1,0]
	v_pk_mul_f32 v[128:129], v[128:129], v[152:153] op_sel_hi:[1,0]
	v_pk_mul_f32 v[122:123], v[122:123], v[152:153] op_sel_hi:[1,0]
	v_pk_mul_f32 v[124:125], v[124:125], v[152:153] op_sel_hi:[1,0]
	ds_swizzle_b32 v114, v126 offset:0x401f
	ds_swizzle_b32 v115, v127 offset:0x401f
	ds_swizzle_b32 v116, v128 offset:0x401f
	ds_swizzle_b32 v117, v129 offset:0x401f
	s_waitcnt vmcnt(4)
	v_xor_b32_e32 v162, v201, v162
	v_xor_b32_e32 v163, v201, v163
	v_xor_b32_e32 v164, v201, v164
	v_xor_b32_e32 v165, v201, v165
	v_xor_b32_e32 v166, v201, v166
	v_xor_b32_e32 v167, v201, v167
	v_xor_b32_e32 v168, v201, v168
	v_xor_b32_e32 v169, v201, v169
	s_waitcnt lgkmcnt(0)
	v_mul_f32_e32 v114, v162, v114
	v_fmac_f32_e32 v114, v126, v154
	v_cndmask_b32_e64 v126, v126, v114, s[38:39]
	v_mul_f32_e32 v115, v163, v115
	v_fmac_f32_e32 v115, v127, v155
	v_cndmask_b32_e64 v127, v127, v115, s[38:39]
	v_mul_f32_e32 v116, v164, v116
	v_fmac_f32_e32 v116, v128, v156
	v_cndmask_b32_e64 v128, v128, v116, s[38:39]
	v_mul_f32_e32 v117, v165, v117
	v_fmac_f32_e32 v117, v129, v157
	v_cndmask_b32_e64 v129, v129, v117, s[38:39]
	ds_swizzle_b32 v114, v122 offset:0x401f
	ds_swizzle_b32 v115, v123 offset:0x401f
	ds_swizzle_b32 v116, v124 offset:0x401f
	ds_swizzle_b32 v117, v125 offset:0x401f
	s_waitcnt lgkmcnt(0)
;     __device__ __forceinline__ void operator()(const f32x4 (&acc)[2][2][4][2], const Unit& u, int wr, int wc, int fr, int fq, PG8_LAS float* stash, int par, PG8_LAS unsigned char* stg, const Unit& un) const {
;     ...
;                     for (int i = 0; i < 4; ++i) { v[i] = acc[ai][bj][m][0][i] * rs; v[4 + i] = acc[ai][bj][m][1][i] * rs; }
;                     if (kind <= 1 && bj == 0) {
;                         const f32x4 c0 = *(const f32x4*)(cs + pos * 16), c1 = *(const f32x4*)(cs + pos * 16 + 4), s0 = *(const f32x4*)(cs + pos * 16 + 8), s1 = *(const f32x4*)(cs + pos * 16 + 12);
; #pragma unroll
;                         for (int i = 0; i < 8; ++i) {
;                             const float c = i < 4 ? c0[i & 3] : c1[i & 3], s = i < 4 ? s0[i & 3] : s1[i & 3];
;                             const float pr = peer_x16(v[i], fq);
;                             const float r = (fq == 0) ? (v[i] * c - pr * s) : (v[i] * c + pr * s);
;                             v[i] = (fq < 2) ? r : v[i];
;                         }
;                     }
;                     if (kind == 0) {
; #pragma unroll
;                         for (int i = 0; i < 8; ++i) v[i] *= C2Q;
;                     }
;                     { u32x4 w; w.x = cvt_pk_bf16(v[0], v[1]); w.y = cvt_pk_bf16(v[2], v[3]); w.z = cvt_pk_bf16(v[4], v[5]); w.w = cvt_pk_bf16(v[6], v[7]);
;                       *(PG8_LAS u32x4*)(stg + fr * 144 + fq * 16 + bj * 64) = w; }
;                 }
;                 {
;                     int kind;
;                     if (odd) kind = (u.pn < 6) ? 0 : (u.pn == 6 ? 1 : 2);
;                     else     kind = (u.pn < 2) ? 0 : (u.pn == 2 ? (wc < 2 ? 1 : 2) : 3);
; #pragma unroll
;                     for (int i = 0; i < 2; ++i) { const int c = fq * 16 + fr + 64 * i, rr = c >> 3, pc = c & 7;
;                         const u32x4 w = *(const PG8_LAS u32x4*)(stg + rr * 144 + pc * 16);
;                         const int rowc = row - fr + rr, posc = rowc & 4095;
;                         if (kind == 1 || kind == 2) {
;                             bf16_t* dst = (kind == 1) ? kd : vt;
;                             if (odd) *(u32x4*)(dst + (size_t)(b * 4 + wc) * (4096 * 64) + (size_t)((posc & 15) * 256 + (posc >> 4)) * 64 + pc * 8) = w;
;                             else     *(u32x4*)(dst + (size_t)(b * 2 + (wc & 1)) * (4096 * 64) + (size_t)posc * 64 + pc * 8) = w;
	v_mul_f32_e32 v114, v166, v114
	v_fmac_f32_e32 v114, v122, v158
	v_cndmask_b32_e64 v122, v122, v114, s[38:39]
	v_mul_f32_e32 v115, v167, v115
	v_fmac_f32_e32 v115, v123, v159
	v_cndmask_b32_e64 v123, v123, v115, s[38:39]
	v_mul_f32_e32 v116, v168, v116
	v_fmac_f32_e32 v116, v124, v160
	v_cndmask_b32_e64 v124, v124, v116, s[38:39]
	v_mul_f32_e32 v117, v169, v117
	v_fmac_f32_e32 v117, v125, v161
	v_cndmask_b32_e64 v125, v125, v117, s[38:39]
	v_cvt_pk_bf16_f32 v126, v126, v127
	v_cvt_pk_bf16_f32 v127, v128, v129
	v_cvt_pk_bf16_f32 v128, v122, v123
	v_cvt_pk_bf16_f32 v129, v124, v125
	ds_write_b128 v178, v[126:129]
	ds_write_b128 v178, v[118:121] offset:64
	ds_read_b128 v[122:125], v180
	ds_read_b128 v[114:117], v180 offset:1152
	s_add_i32 s44, s19, 32
	s_and_b32 s44, s44, 0xfff
	v_or_b32_e32 v0, s44, v141
	v_lshlrev_b32_e32 v0, 6, v0
	s_mov_b64 s[44:45], exec
	s_and_b64 exec, exec, s[38:39]
	global_load_dwordx4 v[154:157], v0, s[62:63]
	global_load_dwordx4 v[158:161], v0, s[62:63] offset:16
	global_load_dwordx4 v[162:165], v0, s[62:63] offset:32
	global_load_dwordx4 v[166:169], v0, s[62:63] offset:48
	s_mov_b64 exec, s[44:45]
	v_pk_mul_f32 v[102:103], v[102:103], v[152:153] op_sel:[0,1]
	v_pk_mul_f32 v[104:105], v[104:105], v[152:153] op_sel:[0,1]
	v_pk_mul_f32 v[98:99], v[98:99], v[152:153] op_sel:[0,1]
	v_pk_mul_f32 v[100:101], v[100:101], v[152:153] op_sel:[0,1]
	v_cvt_pk_bf16_f32 v102, v102, v103
	v_cvt_pk_bf16_f32 v103, v104, v105
	v_cvt_pk_bf16_f32 v104, v98, v99
	v_cvt_pk_bf16_f32 v105, v100, v101
	v_pk_mul_f32 v[110:111], v[110:111], v[152:153] op_sel:[0,1]
	v_pk_mul_f32 v[112:113], v[112:113], v[152:153] op_sel:[0,1]
	v_pk_mul_f32 v[106:107], v[106:107], v[152:153] op_sel:[0,1]
	v_pk_mul_f32 v[108:109], v[108:109], v[152:153] op_sel:[0,1]
	ds_swizzle_b32 v98, v110 offset:0x401f
	ds_swizzle_b32 v99, v111 offset:0x401f
	ds_swizzle_b32 v100, v112 offset:0x401f
	ds_swizzle_b32 v101, v113 offset:0x401f
	s_waitcnt vmcnt(4)
	v_xor_b32_e32 v226, v201, v226
	v_xor_b32_e32 v227, v201, v227
	v_xor_b32_e32 v228, v201, v228
	v_xor_b32_e32 v229, v201, v229
	v_xor_b32_e32 v230, v201, v230
	v_xor_b32_e32 v231, v201, v231
	v_xor_b32_e32 v232, v201, v232
	v_xor_b32_e32 v233, v201, v233
	s_waitcnt lgkmcnt(0)
	v_mul_f32_e32 v98, v226, v98
	v_fmac_f32_e32 v98, v110, v218
	v_cndmask_b32_e64 v110, v110, v98, s[38:39]
	v_mul_f32_e32 v99, v227, v99
	v_fmac_f32_e32 v99, v111, v219
	v_cndmask_b32_e64 v111, v111, v99, s[38:39]
	v_mul_f32_e32 v100, v228, v100
	v_fmac_f32_e32 v100, v112, v220
	v_cndmask_b32_e64 v112, v112, v100, s[38:39]
	v_mul_f32_e32 v101, v229, v101
	v_fmac_f32_e32 v101, v113, v221
	v_cndmask_b32_e64 v113, v113, v101, s[38:39]
	ds_swizzle_b32 v98, v106 offset:0x401f
	ds_swizzle_b32 v99, v107 offset:0x401f
	ds_swizzle_b32 v100, v108 offset:0x401f
	ds_swizzle_b32 v101, v109 offset:0x401f
	s_waitcnt lgkmcnt(0)
	v_mul_f32_e32 v98, v230, v98
	v_fmac_f32_e32 v98, v106, v222
	v_cndmask_b32_e64 v106, v106, v98, s[38:39]
	v_mul_f32_e32 v99, v231, v99
	v_fmac_f32_e32 v99, v107, v223
	v_cndmask_b32_e64 v107, v107, v99, s[38:39]
	v_mul_f32_e32 v100, v232, v100
	v_fmac_f32_e32 v100, v108, v224
	v_cndmask_b32_e64 v108, v108, v100, s[38:39]
	v_mul_f32_e32 v101, v233, v101
	v_fmac_f32_e32 v101, v109, v225
	v_cndmask_b32_e64 v109, v109, v101, s[38:39]
	v_cvt_pk_bf16_f32 v110, v110, v111
	v_cvt_pk_bf16_f32 v111, v112, v113
	v_cvt_pk_bf16_f32 v112, v106, v107
	v_cvt_pk_bf16_f32 v113, v108, v109
	s_mov_b32 s100, s98
	s_mov_b32 s101, s99
	global_store_dwordx4 v200, v[122:125], s[100:101] nt
	s_add_u32 s100, s100, s67
	s_addc_u32 s101, s101, 0
	global_store_dwordx4 v200, v[114:117], s[100:101] nt
	ds_write_b128 v178, v[110:113]
	ds_write_b128 v178, v[102:105] offset:64
	ds_read_b128 v[106:109], v180
	ds_read_b128 v[98:101], v180 offset:1152
	s_add_i32 s44, s19, 48
	s_and_b32 s44, s44, 0xfff
	v_or_b32_e32 v0, s44, v141
	v_lshlrev_b32_e32 v0, 6, v0
	s_mov_b64 s[44:45], exec
	s_and_b64 exec, exec, s[38:39]
	global_load_dwordx4 v[218:221], v0, s[62:63]
	global_load_dwordx4 v[222:225], v0, s[62:63] offset:16
	global_load_dwordx4 v[226:229], v0, s[62:63] offset:32
	global_load_dwordx4 v[230:233], v0, s[62:63] offset:48
	s_mov_b64 exec, s[44:45]
	v_pk_mul_f32 v[86:87], v[86:87], v[150:151] op_sel_hi:[1,0]
	v_pk_mul_f32 v[88:89], v[88:89], v[150:151] op_sel_hi:[1,0]
	v_pk_mul_f32 v[82:83], v[82:83], v[150:151] op_sel_hi:[1,0]
	v_pk_mul_f32 v[84:85], v[84:85], v[150:151] op_sel_hi:[1,0]
	v_cvt_pk_bf16_f32 v86, v86, v87
	v_cvt_pk_bf16_f32 v87, v88, v89
	v_cvt_pk_bf16_f32 v88, v82, v83
	v_cvt_pk_bf16_f32 v89, v84, v85
	v_pk_mul_f32 v[94:95], v[94:95], v[150:151] op_sel_hi:[1,0]
	v_pk_mul_f32 v[96:97], v[96:97], v[150:151] op_sel_hi:[1,0]
	v_pk_mul_f32 v[90:91], v[90:91], v[150:151] op_sel_hi:[1,0]
	v_pk_mul_f32 v[92:93], v[92:93], v[150:151] op_sel_hi:[1,0]
	ds_swizzle_b32 v82, v94 offset:0x401f
	ds_swizzle_b32 v83, v95 offset:0x401f
	ds_swizzle_b32 v84, v96 offset:0x401f
	ds_swizzle_b32 v85, v97 offset:0x401f
	s_waitcnt vmcnt(6)
	v_xor_b32_e32 v162, v201, v162
	v_xor_b32_e32 v163, v201, v163
	v_xor_b32_e32 v164, v201, v164
	v_xor_b32_e32 v165, v201, v165
	v_xor_b32_e32 v166, v201, v166
	v_xor_b32_e32 v167, v201, v167
	v_xor_b32_e32 v168, v201, v168
	v_xor_b32_e32 v169, v201, v169
	s_waitcnt lgkmcnt(0)
	v_mul_f32_e32 v82, v162, v82
	v_fmac_f32_e32 v82, v94, v154
	v_cndmask_b32_e64 v94, v94, v82, s[38:39]
	v_mul_f32_e32 v83, v163, v83
	v_fmac_f32_e32 v83, v95, v155
	v_cndmask_b32_e64 v95, v95, v83, s[38:39]
	v_mul_f32_e32 v84, v164, v84
	v_fmac_f32_e32 v84, v96, v156
	v_cndmask_b32_e64 v96, v96, v84, s[38:39]
	v_mul_f32_e32 v85, v165, v85
	v_fmac_f32_e32 v85, v97, v157
	v_cndmask_b32_e64 v97, v97, v85, s[38:39]
	ds_swizzle_b32 v82, v90 offset:0x401f
	ds_swizzle_b32 v83, v91 offset:0x401f
	ds_swizzle_b32 v84, v92 offset:0x401f
	ds_swizzle_b32 v85, v93 offset:0x401f
	s_waitcnt lgkmcnt(0)
;     __device__ __forceinline__ void operator()(const f32x4 (&acc)[2][2][4][2], const Unit& u, int wr, int wc, int fr, int fq, PG8_LAS float* stash, int par, PG8_LAS unsigned char* stg, const Unit& un) const {
;     ...
;                     for (int i = 0; i < 4; ++i) { v[i] = acc[ai][bj][m][0][i] * rs; v[4 + i] = acc[ai][bj][m][1][i] * rs; }
;                     if (kind <= 1 && bj == 0) {
;                         const f32x4 c0 = *(const f32x4*)(cs + pos * 16), c1 = *(const f32x4*)(cs + pos * 16 + 4), s0 = *(const f32x4*)(cs + pos * 16 + 8), s1 = *(const f32x4*)(cs + pos * 16 + 12);
; #pragma unroll
;                         for (int i = 0; i < 8; ++i) {
;                             const float c = i < 4 ? c0[i & 3] : c1[i & 3], s = i < 4 ? s0[i & 3] : s1[i & 3];
;                             const float pr = peer_x16(v[i], fq);
;                             const float r = (fq == 0) ? (v[i] * c - pr * s) : (v[i] * c + pr * s);
;                             v[i] = (fq < 2) ? r : v[i];
;                         }
;                     }
;                     if (kind == 0) {
; #pragma unroll
;                         for (int i = 0; i < 8; ++i) v[i] *= C2Q;
;                     }
;                     { u32x4 w; w.x = cvt_pk_bf16(v[0], v[1]); w.y = cvt_pk_bf16(v[2], v[3]); w.z = cvt_pk_bf16(v[4], v[5]); w.w = cvt_pk_bf16(v[6], v[7]);
;                       *(PG8_LAS u32x4*)(stg + fr * 144 + fq * 16 + bj * 64) = w; }
;                 }
;                 {
;                     int kind;
;                     if (odd) kind = (u.pn < 6) ? 0 : (u.pn == 6 ? 1 : 2);
;                     else     kind = (u.pn < 2) ? 0 : (u.pn == 2 ? (wc < 2 ? 1 : 2) : 3);
; #pragma unroll
;                     for (int i = 0; i < 2; ++i) { const int c = fq * 16 + fr + 64 * i, rr = c >> 3, pc = c & 7;
;                         const u32x4 w = *(const PG8_LAS u32x4*)(stg + rr * 144 + pc * 16);
;                         const int rowc = row - fr + rr, posc = rowc & 4095;
;                         if (kind == 1 || kind == 2) {
;                             bf16_t* dst = (kind == 1) ? kd : vt;
;                             if (odd) *(u32x4*)(dst + (size_t)(b * 4 + wc) * (4096 * 64) + (size_t)((posc & 15) * 256 + (posc >> 4)) * 64 + pc * 8) = w;
;                             else     *(u32x4*)(dst + (size_t)(b * 2 + (wc & 1)) * (4096 * 64) + (size_t)posc * 64 + pc * 8) = w;
	v_mul_f32_e32 v82, v166, v82
	v_fmac_f32_e32 v82, v90, v158
	v_cndmask_b32_e64 v90, v90, v82, s[38:39]
	v_mul_f32_e32 v83, v167, v83
	v_fmac_f32_e32 v83, v91, v159
	v_cndmask_b32_e64 v91, v91, v83, s[38:39]
	v_mul_f32_e32 v84, v168, v84
	v_fmac_f32_e32 v84, v92, v160
	v_cndmask_b32_e64 v92, v92, v84, s[38:39]
	v_mul_f32_e32 v85, v169, v85
	v_fmac_f32_e32 v85, v93, v161
	v_cndmask_b32_e64 v93, v93, v85, s[38:39]
	v_cvt_pk_bf16_f32 v94, v94, v95
	v_cvt_pk_bf16_f32 v95, v96, v97
	v_cvt_pk_bf16_f32 v96, v90, v91
	v_cvt_pk_bf16_f32 v97, v92, v93
	s_mul_i32 s44, s66, 16
	s_add_u32 s100, s98, s44
	s_addc_u32 s101, s99, 0
	global_store_dwordx4 v200, v[106:109], s[100:101] nt
	s_add_u32 s100, s100, s67
	s_addc_u32 s101, s101, 0
	global_store_dwordx4 v200, v[98:101], s[100:101] nt
	ds_write_b128 v178, v[94:97]
	ds_write_b128 v178, v[86:89] offset:64
	ds_read_b128 v[90:93], v180
	ds_read_b128 v[82:85], v180 offset:1152
	s_add_i32 s44, s19, 128
	s_and_b32 s44, s44, 0xfff
	v_or_b32_e32 v0, s44, v141
	v_lshlrev_b32_e32 v0, 6, v0
	s_mov_b64 s[44:45], exec
	s_and_b64 exec, exec, s[38:39]
	global_load_dwordx4 v[154:157], v0, s[62:63]
	global_load_dwordx4 v[158:161], v0, s[62:63] offset:16
	global_load_dwordx4 v[162:165], v0, s[62:63] offset:32
	global_load_dwordx4 v[166:169], v0, s[62:63] offset:48
	s_mov_b64 exec, s[44:45]
	v_pk_mul_f32 v[70:71], v[70:71], v[150:151] op_sel:[0,1]
	v_pk_mul_f32 v[72:73], v[72:73], v[150:151] op_sel:[0,1]
	v_pk_mul_f32 v[66:67], v[66:67], v[150:151] op_sel:[0,1]
	v_pk_mul_f32 v[68:69], v[68:69], v[150:151] op_sel:[0,1]
	v_cvt_pk_bf16_f32 v70, v70, v71
	v_cvt_pk_bf16_f32 v71, v72, v73
	v_cvt_pk_bf16_f32 v72, v66, v67
	v_cvt_pk_bf16_f32 v73, v68, v69
	v_pk_mul_f32 v[78:79], v[78:79], v[150:151] op_sel:[0,1]
	v_pk_mul_f32 v[80:81], v[80:81], v[150:151] op_sel:[0,1]
	v_pk_mul_f32 v[74:75], v[74:75], v[150:151] op_sel:[0,1]
	v_pk_mul_f32 v[76:77], v[76:77], v[150:151] op_sel:[0,1]
	ds_swizzle_b32 v66, v78 offset:0x401f
	ds_swizzle_b32 v67, v79 offset:0x401f
	ds_swizzle_b32 v68, v80 offset:0x401f
	ds_swizzle_b32 v69, v81 offset:0x401f
	s_waitcnt vmcnt(6)
	v_xor_b32_e32 v226, v201, v226
	v_xor_b32_e32 v227, v201, v227
	v_xor_b32_e32 v228, v201, v228
	v_xor_b32_e32 v229, v201, v229
	v_xor_b32_e32 v230, v201, v230
	v_xor_b32_e32 v231, v201, v231
	v_xor_b32_e32 v232, v201, v232
	v_xor_b32_e32 v233, v201, v233
	s_waitcnt lgkmcnt(0)
	v_mul_f32_e32 v66, v226, v66
	v_fmac_f32_e32 v66, v78, v218
	v_cndmask_b32_e64 v78, v78, v66, s[38:39]
	v_mul_f32_e32 v67, v227, v67
	v_fmac_f32_e32 v67, v79, v219
	v_cndmask_b32_e64 v79, v79, v67, s[38:39]
	v_mul_f32_e32 v68, v228, v68
	v_fmac_f32_e32 v68, v80, v220
	v_cndmask_b32_e64 v80, v80, v68, s[38:39]
	v_mul_f32_e32 v69, v229, v69
	v_fmac_f32_e32 v69, v81, v221
	v_cndmask_b32_e64 v81, v81, v69, s[38:39]
	ds_swizzle_b32 v66, v74 offset:0x401f
	ds_swizzle_b32 v67, v75 offset:0x401f
	ds_swizzle_b32 v68, v76 offset:0x401f
	ds_swizzle_b32 v69, v77 offset:0x401f
	s_waitcnt lgkmcnt(0)
	v_mul_f32_e32 v66, v230, v66
	v_fmac_f32_e32 v66, v74, v222
	v_cndmask_b32_e64 v74, v74, v66, s[38:39]
	v_mul_f32_e32 v67, v231, v67
	v_fmac_f32_e32 v67, v75, v223
	v_cndmask_b32_e64 v75, v75, v67, s[38:39]
	v_mul_f32_e32 v68, v232, v68
	v_fmac_f32_e32 v68, v76, v224
	v_cndmask_b32_e64 v76, v76, v68, s[38:39]
	v_mul_f32_e32 v69, v233, v69
	v_fmac_f32_e32 v69, v77, v225
	v_cndmask_b32_e64 v77, v77, v69, s[38:39]
	v_cvt_pk_bf16_f32 v78, v78, v79
	v_cvt_pk_bf16_f32 v79, v80, v81
	v_cvt_pk_bf16_f32 v80, v74, v75
	v_cvt_pk_bf16_f32 v81, v76, v77
	s_mul_i32 s44, s66, 32
	s_add_u32 s100, s98, s44
	s_addc_u32 s101, s99, 0
	global_store_dwordx4 v200, v[90:93], s[100:101] nt
	s_add_u32 s100, s100, s67
	s_addc_u32 s101, s101, 0
	global_store_dwordx4 v200, v[82:85], s[100:101] nt
	ds_write_b128 v178, v[78:81]
	ds_write_b128 v178, v[70:73] offset:64
	ds_read_b128 v[74:77], v180
	ds_read_b128 v[66:69], v180 offset:1152
	s_add_i32 s44, s19, 144
	s_and_b32 s44, s44, 0xfff
	v_or_b32_e32 v0, s44, v141
	v_lshlrev_b32_e32 v0, 6, v0
	s_mov_b64 s[44:45], exec
	s_and_b64 exec, exec, s[38:39]
	global_load_dwordx4 v[218:221], v0, s[62:63]
	global_load_dwordx4 v[222:225], v0, s[62:63] offset:16
	global_load_dwordx4 v[226:229], v0, s[62:63] offset:32
	global_load_dwordx4 v[230:233], v0, s[62:63] offset:48
	s_mov_b64 exec, s[44:45]
	v_pk_mul_f32 v[54:55], v[54:55], v[148:149] op_sel_hi:[1,0]
	v_pk_mul_f32 v[56:57], v[56:57], v[148:149] op_sel_hi:[1,0]
	v_pk_mul_f32 v[50:51], v[50:51], v[148:149] op_sel_hi:[1,0]
	v_pk_mul_f32 v[52:53], v[52:53], v[148:149] op_sel_hi:[1,0]
	v_cvt_pk_bf16_f32 v54, v54, v55
	v_cvt_pk_bf16_f32 v55, v56, v57
	v_cvt_pk_bf16_f32 v56, v50, v51
	v_cvt_pk_bf16_f32 v57, v52, v53
	v_pk_mul_f32 v[62:63], v[62:63], v[148:149] op_sel_hi:[1,0]
	v_pk_mul_f32 v[64:65], v[64:65], v[148:149] op_sel_hi:[1,0]
	v_pk_mul_f32 v[58:59], v[58:59], v[148:149] op_sel_hi:[1,0]
	v_pk_mul_f32 v[60:61], v[60:61], v[148:149] op_sel_hi:[1,0]
	ds_swizzle_b32 v50, v62 offset:0x401f
	ds_swizzle_b32 v51, v63 offset:0x401f
	ds_swizzle_b32 v52, v64 offset:0x401f
	ds_swizzle_b32 v53, v65 offset:0x401f
	s_waitcnt vmcnt(6)
	v_xor_b32_e32 v162, v201, v162
	v_xor_b32_e32 v163, v201, v163
	v_xor_b32_e32 v164, v201, v164
	v_xor_b32_e32 v165, v201, v165
	v_xor_b32_e32 v166, v201, v166
	v_xor_b32_e32 v167, v201, v167
	v_xor_b32_e32 v168, v201, v168
	v_xor_b32_e32 v169, v201, v169
	s_waitcnt lgkmcnt(0)
;     __device__ __forceinline__ void operator()(const f32x4 (&acc)[2][2][4][2], const Unit& u, int wr, int wc, int fr, int fq, PG8_LAS float* stash, int par, PG8_LAS unsigned char* stg, const Unit& un) const {
;     ...
;                     for (int i = 0; i < 4; ++i) { v[i] = acc[ai][bj][m][0][i] * rs; v[4 + i] = acc[ai][bj][m][1][i] * rs; }
;                     if (kind <= 1 && bj == 0) {
;                         const f32x4 c0 = *(const f32x4*)(cs + pos * 16), c1 = *(const f32x4*)(cs + pos * 16 + 4), s0 = *(const f32x4*)(cs + pos * 16 + 8), s1 = *(const f32x4*)(cs + pos * 16 + 12);
; #pragma unroll
;                         for (int i = 0; i < 8; ++i) {
;                             const float c = i < 4 ? c0[i & 3] : c1[i & 3], s = i < 4 ? s0[i & 3] : s1[i & 3];
;                             const float pr = peer_x16(v[i], fq);
;                             const float r = (fq == 0) ? (v[i] * c - pr * s) : (v[i] * c + pr * s);
;                             v[i] = (fq < 2) ? r : v[i];
;                         }
;                     }
;                     if (kind == 0) {
; #pragma unroll
;                         for (int i = 0; i < 8; ++i) v[i] *= C2Q;
;                     }
;                     { u32x4 w; w.x = cvt_pk_bf16(v[0], v[1]); w.y = cvt_pk_bf16(v[2], v[3]); w.z = cvt_pk_bf16(v[4], v[5]); w.w = cvt_pk_bf16(v[6], v[7]);
;                       *(PG8_LAS u32x4*)(stg + fr * 144 + fq * 16 + bj * 64) = w; }
;                 }
;                 {
;                     int kind;
;                     if (odd) kind = (u.pn < 6) ? 0 : (u.pn == 6 ? 1 : 2);
;                     else     kind = (u.pn < 2) ? 0 : (u.pn == 2 ? (wc < 2 ? 1 : 2) : 3);
; #pragma unroll
;                     for (int i = 0; i < 2; ++i) { const int c = fq * 16 + fr + 64 * i, rr = c >> 3, pc = c & 7;
;                         const u32x4 w = *(const PG8_LAS u32x4*)(stg + rr * 144 + pc * 16);
;                         const int rowc = row - fr + rr, posc = rowc & 4095;
;                         if (kind == 1 || kind == 2) {
;                             bf16_t* dst = (kind == 1) ? kd : vt;
;                             if (odd) *(u32x4*)(dst + (size_t)(b * 4 + wc) * (4096 * 64) + (size_t)((posc & 15) * 256 + (posc >> 4)) * 64 + pc * 8) = w;
;                             else     *(u32x4*)(dst + (size_t)(b * 2 + (wc & 1)) * (4096 * 64) + (size_t)posc * 64 + pc * 8) = w;
	v_mul_f32_e32 v50, v162, v50
	v_fmac_f32_e32 v50, v62, v154
	v_cndmask_b32_e64 v62, v62, v50, s[38:39]
	v_mul_f32_e32 v51, v163, v51
	v_fmac_f32_e32 v51, v63, v155
	v_cndmask_b32_e64 v63, v63, v51, s[38:39]
	v_mul_f32_e32 v52, v164, v52
	v_fmac_f32_e32 v52, v64, v156
	v_cndmask_b32_e64 v64, v64, v52, s[38:39]
	v_mul_f32_e32 v53, v165, v53
	v_fmac_f32_e32 v53, v65, v157
	v_cndmask_b32_e64 v65, v65, v53, s[38:39]
	ds_swizzle_b32 v50, v58 offset:0x401f
	ds_swizzle_b32 v51, v59 offset:0x401f
	ds_swizzle_b32 v52, v60 offset:0x401f
	ds_swizzle_b32 v53, v61 offset:0x401f
	s_waitcnt lgkmcnt(0)
	v_mul_f32_e32 v50, v166, v50
	v_fmac_f32_e32 v50, v58, v158
	v_cndmask_b32_e64 v58, v58, v50, s[38:39]
	v_mul_f32_e32 v51, v167, v51
	v_fmac_f32_e32 v51, v59, v159
	v_cndmask_b32_e64 v59, v59, v51, s[38:39]
	v_mul_f32_e32 v52, v168, v52
	v_fmac_f32_e32 v52, v60, v160
	v_cndmask_b32_e64 v60, v60, v52, s[38:39]
	v_mul_f32_e32 v53, v169, v53
	v_fmac_f32_e32 v53, v61, v161
	v_cndmask_b32_e64 v61, v61, v53, s[38:39]
	v_cvt_pk_bf16_f32 v62, v62, v63
	v_cvt_pk_bf16_f32 v63, v64, v65
	v_cvt_pk_bf16_f32 v64, v58, v59
	v_cvt_pk_bf16_f32 v65, v60, v61
	s_mul_i32 s44, s66, 48
	s_add_u32 s100, s98, s44
	s_addc_u32 s101, s99, 0
	global_store_dwordx4 v200, v[74:77], s[100:101] nt
	s_add_u32 s100, s100, s67
	s_addc_u32 s101, s101, 0
	global_store_dwordx4 v200, v[66:69], s[100:101] nt
	ds_write_b128 v178, v[62:65]
	ds_write_b128 v178, v[54:57] offset:64
	ds_read_b128 v[58:61], v180
	ds_read_b128 v[50:53], v180 offset:1152
	s_add_i32 s44, s19, 160
	s_and_b32 s44, s44, 0xfff
	v_or_b32_e32 v0, s44, v141
	v_lshlrev_b32_e32 v0, 6, v0
	s_mov_b64 s[44:45], exec
	s_and_b64 exec, exec, s[38:39]
	global_load_dwordx4 v[154:157], v0, s[62:63]
	global_load_dwordx4 v[158:161], v0, s[62:63] offset:16
	global_load_dwordx4 v[162:165], v0, s[62:63] offset:32
	global_load_dwordx4 v[166:169], v0, s[62:63] offset:48
	s_mov_b64 exec, s[44:45]
	v_pk_mul_f32 v[38:39], v[38:39], v[148:149] op_sel:[0,1]
	v_pk_mul_f32 v[40:41], v[40:41], v[148:149] op_sel:[0,1]
	v_pk_mul_f32 v[34:35], v[34:35], v[148:149] op_sel:[0,1]
	v_pk_mul_f32 v[36:37], v[36:37], v[148:149] op_sel:[0,1]
	v_cvt_pk_bf16_f32 v38, v38, v39
	v_cvt_pk_bf16_f32 v39, v40, v41
	v_cvt_pk_bf16_f32 v40, v34, v35
	v_cvt_pk_bf16_f32 v41, v36, v37
	v_pk_mul_f32 v[46:47], v[46:47], v[148:149] op_sel:[0,1]
	v_pk_mul_f32 v[48:49], v[48:49], v[148:149] op_sel:[0,1]
	v_pk_mul_f32 v[42:43], v[42:43], v[148:149] op_sel:[0,1]
	v_pk_mul_f32 v[44:45], v[44:45], v[148:149] op_sel:[0,1]
	ds_swizzle_b32 v34, v46 offset:0x401f
	ds_swizzle_b32 v35, v47 offset:0x401f
	ds_swizzle_b32 v36, v48 offset:0x401f
	ds_swizzle_b32 v37, v49 offset:0x401f
	s_waitcnt vmcnt(6)
	v_xor_b32_e32 v226, v201, v226
	v_xor_b32_e32 v227, v201, v227
	v_xor_b32_e32 v228, v201, v228
	v_xor_b32_e32 v229, v201, v229
	v_xor_b32_e32 v230, v201, v230
	v_xor_b32_e32 v231, v201, v231
	v_xor_b32_e32 v232, v201, v232
	v_xor_b32_e32 v233, v201, v233
	s_waitcnt lgkmcnt(0)
	v_mul_f32_e32 v34, v226, v34
	v_fmac_f32_e32 v34, v46, v218
	v_cndmask_b32_e64 v46, v46, v34, s[38:39]
	v_mul_f32_e32 v35, v227, v35
	v_fmac_f32_e32 v35, v47, v219
	v_cndmask_b32_e64 v47, v47, v35, s[38:39]
	v_mul_f32_e32 v36, v228, v36
	v_fmac_f32_e32 v36, v48, v220
	v_cndmask_b32_e64 v48, v48, v36, s[38:39]
	v_mul_f32_e32 v37, v229, v37
	v_fmac_f32_e32 v37, v49, v221
	v_cndmask_b32_e64 v49, v49, v37, s[38:39]
	ds_swizzle_b32 v34, v42 offset:0x401f
	ds_swizzle_b32 v35, v43 offset:0x401f
	ds_swizzle_b32 v36, v44 offset:0x401f
	ds_swizzle_b32 v37, v45 offset:0x401f
	s_waitcnt lgkmcnt(0)
	v_mul_f32_e32 v34, v230, v34
	v_fmac_f32_e32 v34, v42, v222
	v_cndmask_b32_e64 v42, v42, v34, s[38:39]
	v_mul_f32_e32 v35, v231, v35
	v_fmac_f32_e32 v35, v43, v223
	v_cndmask_b32_e64 v43, v43, v35, s[38:39]
	v_mul_f32_e32 v36, v232, v36
	v_fmac_f32_e32 v36, v44, v224
	v_cndmask_b32_e64 v44, v44, v36, s[38:39]
	v_mul_f32_e32 v37, v233, v37
	v_fmac_f32_e32 v37, v45, v225
	v_cndmask_b32_e64 v45, v45, v37, s[38:39]
	v_cvt_pk_bf16_f32 v46, v46, v47
	v_cvt_pk_bf16_f32 v47, v48, v49
	v_cvt_pk_bf16_f32 v48, v42, v43
	v_cvt_pk_bf16_f32 v49, v44, v45
	s_mul_i32 s44, s66, 128
	s_add_u32 s100, s98, s44
	s_addc_u32 s101, s99, 0
	global_store_dwordx4 v200, v[58:61], s[100:101] nt
	s_add_u32 s100, s100, s67
	s_addc_u32 s101, s101, 0
	global_store_dwordx4 v200, v[50:53], s[100:101] nt
	ds_write_b128 v178, v[46:49]
	ds_write_b128 v178, v[38:41] offset:64
	ds_read_b128 v[42:45], v180
	ds_read_b128 v[34:37], v180 offset:1152
	s_add_i32 s44, s19, 176
	s_and_b32 s44, s44, 0xfff
	v_or_b32_e32 v0, s44, v141
	v_lshlrev_b32_e32 v0, 6, v0
	s_mov_b64 s[44:45], exec
	s_and_b64 exec, exec, s[38:39]
	global_load_dwordx4 v[218:221], v0, s[62:63]
	global_load_dwordx4 v[222:225], v0, s[62:63] offset:16
	global_load_dwordx4 v[226:229], v0, s[62:63] offset:32
	global_load_dwordx4 v[230:233], v0, s[62:63] offset:48
	s_mov_b64 exec, s[44:45]
	v_pk_mul_f32 v[22:23], v[22:23], v[146:147] op_sel_hi:[1,0]
	v_pk_mul_f32 v[24:25], v[24:25], v[146:147] op_sel_hi:[1,0]
	v_pk_mul_f32 v[18:19], v[18:19], v[146:147] op_sel_hi:[1,0]
	v_pk_mul_f32 v[20:21], v[20:21], v[146:147] op_sel_hi:[1,0]
	v_cvt_pk_bf16_f32 v22, v22, v23
	v_cvt_pk_bf16_f32 v23, v24, v25
	v_cvt_pk_bf16_f32 v24, v18, v19
	v_cvt_pk_bf16_f32 v25, v20, v21
	v_pk_mul_f32 v[30:31], v[30:31], v[146:147] op_sel_hi:[1,0]
	v_pk_mul_f32 v[32:33], v[32:33], v[146:147] op_sel_hi:[1,0]
	v_pk_mul_f32 v[26:27], v[26:27], v[146:147] op_sel_hi:[1,0]
	v_pk_mul_f32 v[28:29], v[28:29], v[146:147] op_sel_hi:[1,0]
	ds_swizzle_b32 v18, v30 offset:0x401f
	ds_swizzle_b32 v19, v31 offset:0x401f
	ds_swizzle_b32 v20, v32 offset:0x401f
	ds_swizzle_b32 v21, v33 offset:0x401f
	s_waitcnt vmcnt(6)
;     __device__ __forceinline__ void operator()(const f32x4 (&acc)[2][2][4][2], const Unit& u, int wr, int wc, int fr, int fq, PG8_LAS float* stash, int par, PG8_LAS unsigned char* stg, const Unit& un) const {
;     ...
;                     for (int i = 0; i < 4; ++i) { v[i] = acc[ai][bj][m][0][i] * rs; v[4 + i] = acc[ai][bj][m][1][i] * rs; }
;                     if (kind <= 1 && bj == 0) {
;                         const f32x4 c0 = *(const f32x4*)(cs + pos * 16), c1 = *(const f32x4*)(cs + pos * 16 + 4), s0 = *(const f32x4*)(cs + pos * 16 + 8), s1 = *(const f32x4*)(cs + pos * 16 + 12);
; #pragma unroll
;                         for (int i = 0; i < 8; ++i) {
;                             const float c = i < 4 ? c0[i & 3] : c1[i & 3], s = i < 4 ? s0[i & 3] : s1[i & 3];
;                             const float pr = peer_x16(v[i], fq);
;                             const float r = (fq == 0) ? (v[i] * c - pr * s) : (v[i] * c + pr * s);
;                             v[i] = (fq < 2) ? r : v[i];
;                         }
;                     }
;                     if (kind == 0) {
; #pragma unroll
;                         for (int i = 0; i < 8; ++i) v[i] *= C2Q;
;                     }
;                     { u32x4 w; w.x = cvt_pk_bf16(v[0], v[1]); w.y = cvt_pk_bf16(v[2], v[3]); w.z = cvt_pk_bf16(v[4], v[5]); w.w = cvt_pk_bf16(v[6], v[7]);
;                       *(PG8_LAS u32x4*)(stg + fr * 144 + fq * 16 + bj * 64) = w; }
;                 }
;                 {
;                     int kind;
;                     if (odd) kind = (u.pn < 6) ? 0 : (u.pn == 6 ? 1 : 2);
;                     else     kind = (u.pn < 2) ? 0 : (u.pn == 2 ? (wc < 2 ? 1 : 2) : 3);
; #pragma unroll
;                     for (int i = 0; i < 2; ++i) { const int c = fq * 16 + fr + 64 * i, rr = c >> 3, pc = c & 7;
;                         const u32x4 w = *(const PG8_LAS u32x4*)(stg + rr * 144 + pc * 16);
;                         const int rowc = row - fr + rr, posc = rowc & 4095;
;                         if (kind == 1 || kind == 2) {
;                             bf16_t* dst = (kind == 1) ? kd : vt;
;                             if (odd) *(u32x4*)(dst + (size_t)(b * 4 + wc) * (4096 * 64) + (size_t)((posc & 15) * 256 + (posc >> 4)) * 64 + pc * 8) = w;
;                             else     *(u32x4*)(dst + (size_t)(b * 2 + (wc & 1)) * (4096 * 64) + (size_t)posc * 64 + pc * 8) = w;
	v_xor_b32_e32 v162, v201, v162
	v_xor_b32_e32 v163, v201, v163
	v_xor_b32_e32 v164, v201, v164
	v_xor_b32_e32 v165, v201, v165
	v_xor_b32_e32 v166, v201, v166
	v_xor_b32_e32 v167, v201, v167
	v_xor_b32_e32 v168, v201, v168
	v_xor_b32_e32 v169, v201, v169
	s_waitcnt lgkmcnt(0)
	v_mul_f32_e32 v18, v162, v18
	v_fmac_f32_e32 v18, v30, v154
	v_cndmask_b32_e64 v30, v30, v18, s[38:39]
	v_mul_f32_e32 v19, v163, v19
	v_fmac_f32_e32 v19, v31, v155
	v_cndmask_b32_e64 v31, v31, v19, s[38:39]
	v_mul_f32_e32 v20, v164, v20
	v_fmac_f32_e32 v20, v32, v156
	v_cndmask_b32_e64 v32, v32, v20, s[38:39]
	v_mul_f32_e32 v21, v165, v21
	v_fmac_f32_e32 v21, v33, v157
	v_cndmask_b32_e64 v33, v33, v21, s[38:39]
	ds_swizzle_b32 v18, v26 offset:0x401f
	ds_swizzle_b32 v19, v27 offset:0x401f
	ds_swizzle_b32 v20, v28 offset:0x401f
	ds_swizzle_b32 v21, v29 offset:0x401f
	s_waitcnt lgkmcnt(0)
	v_mul_f32_e32 v18, v166, v18
	v_fmac_f32_e32 v18, v26, v158
	v_cndmask_b32_e64 v26, v26, v18, s[38:39]
	v_mul_f32_e32 v19, v167, v19
	v_fmac_f32_e32 v19, v27, v159
	v_cndmask_b32_e64 v27, v27, v19, s[38:39]
	v_mul_f32_e32 v20, v168, v20
	v_fmac_f32_e32 v20, v28, v160
	v_cndmask_b32_e64 v28, v28, v20, s[38:39]
	v_mul_f32_e32 v21, v169, v21
	v_fmac_f32_e32 v21, v29, v161
	v_cndmask_b32_e64 v29, v29, v21, s[38:39]
	v_cvt_pk_bf16_f32 v30, v30, v31
	v_cvt_pk_bf16_f32 v31, v32, v33
	v_cvt_pk_bf16_f32 v32, v26, v27
	v_cvt_pk_bf16_f32 v33, v28, v29
	s_mul_i32 s44, s66, 144
	s_add_u32 s100, s98, s44
	s_addc_u32 s101, s99, 0
	global_store_dwordx4 v200, v[42:45], s[100:101] nt
	s_add_u32 s100, s100, s67
	s_addc_u32 s101, s101, 0
	global_store_dwordx4 v200, v[34:37], s[100:101] nt
	ds_write_b128 v178, v[30:33]
	ds_write_b128 v178, v[22:25] offset:64
	ds_read_b128 v[26:29], v180
	ds_read_b128 v[18:21], v180 offset:1152
	v_pk_mul_f32 v[6:7], v[6:7], v[146:147] op_sel:[0,1]
	v_pk_mul_f32 v[8:9], v[8:9], v[146:147] op_sel:[0,1]
	v_pk_mul_f32 v[2:3], v[2:3], v[146:147] op_sel:[0,1]
	v_pk_mul_f32 v[4:5], v[4:5], v[146:147] op_sel:[0,1]
	v_cvt_pk_bf16_f32 v6, v6, v7
	v_cvt_pk_bf16_f32 v7, v8, v9
	v_cvt_pk_bf16_f32 v8, v2, v3
	v_cvt_pk_bf16_f32 v9, v4, v5
	v_pk_mul_f32 v[14:15], v[14:15], v[146:147] op_sel:[0,1]
	v_pk_mul_f32 v[16:17], v[16:17], v[146:147] op_sel:[0,1]
	v_pk_mul_f32 v[10:11], v[10:11], v[146:147] op_sel:[0,1]
	v_pk_mul_f32 v[12:13], v[12:13], v[146:147] op_sel:[0,1]
	ds_swizzle_b32 v2, v14 offset:0x401f
	ds_swizzle_b32 v3, v15 offset:0x401f
	ds_swizzle_b32 v4, v16 offset:0x401f
	ds_swizzle_b32 v5, v17 offset:0x401f
	s_waitcnt vmcnt(2)
	v_xor_b32_e32 v226, v201, v226
	v_xor_b32_e32 v227, v201, v227
	v_xor_b32_e32 v228, v201, v228
	v_xor_b32_e32 v229, v201, v229
	v_xor_b32_e32 v230, v201, v230
	v_xor_b32_e32 v231, v201, v231
	v_xor_b32_e32 v232, v201, v232
	v_xor_b32_e32 v233, v201, v233
	s_waitcnt lgkmcnt(0)
	v_mul_f32_e32 v2, v226, v2
	v_fmac_f32_e32 v2, v14, v218
	v_cndmask_b32_e64 v14, v14, v2, s[38:39]
	v_mul_f32_e32 v3, v227, v3
	v_fmac_f32_e32 v3, v15, v219
	v_cndmask_b32_e64 v15, v15, v3, s[38:39]
	v_mul_f32_e32 v4, v228, v4
	v_fmac_f32_e32 v4, v16, v220
	v_cndmask_b32_e64 v16, v16, v4, s[38:39]
	v_mul_f32_e32 v5, v229, v5
	v_fmac_f32_e32 v5, v17, v221
	v_cndmask_b32_e64 v17, v17, v5, s[38:39]
	ds_swizzle_b32 v2, v10 offset:0x401f
	ds_swizzle_b32 v3, v11 offset:0x401f
	ds_swizzle_b32 v4, v12 offset:0x401f
	ds_swizzle_b32 v5, v13 offset:0x401f
	s_waitcnt lgkmcnt(0)
	v_mul_f32_e32 v2, v230, v2
	v_fmac_f32_e32 v2, v10, v222
	v_cndmask_b32_e64 v10, v10, v2, s[38:39]
	v_mul_f32_e32 v3, v231, v3
	v_fmac_f32_e32 v3, v11, v223
	v_cndmask_b32_e64 v11, v11, v3, s[38:39]
	v_mul_f32_e32 v4, v232, v4
	v_fmac_f32_e32 v4, v12, v224
	v_cndmask_b32_e64 v12, v12, v4, s[38:39]
	v_mul_f32_e32 v5, v233, v5
	v_fmac_f32_e32 v5, v13, v225
	v_cndmask_b32_e64 v13, v13, v5, s[38:39]
	v_cvt_pk_bf16_f32 v14, v14, v15
	v_cvt_pk_bf16_f32 v15, v16, v17
	v_cvt_pk_bf16_f32 v16, v10, v11
	v_cvt_pk_bf16_f32 v17, v12, v13
	s_mul_i32 s44, s66, 160
	s_add_u32 s100, s98, s44
	s_addc_u32 s101, s99, 0
	global_store_dwordx4 v200, v[26:29], s[100:101] nt
	s_add_u32 s100, s100, s67
	s_addc_u32 s101, s101, 0
	global_store_dwordx4 v200, v[18:21], s[100:101] nt
	ds_write_b128 v178, v[14:17]
	ds_write_b128 v178, v[6:9] offset:64
	ds_read_b128 v[10:13], v180
	ds_read_b128 v[2:5], v180 offset:1152
	s_waitcnt lgkmcnt(0)
	s_mul_i32 s44, s66, 176
	s_add_u32 s100, s98, s44
	s_addc_u32 s101, s99, 0
	global_store_dwordx4 v200, v[10:13], s[100:101] nt
	s_add_u32 s100, s100, s67
	s_addc_u32 s101, s101, 0
	global_store_dwordx4 v200, v[2:5], s[100:101] nt
	s_branch .Lipe_done
